# GEMM units: accumulator clears removed; first K-loop trip peeled with SrcC=0 on the first MFMA into each accumulator (on top of barrier TOPGEN poll + zerowait)
# speedup vs baseline: 1.0079x; 1.0022x over previous
; #define PG8_STAGE(bufoff, gbase, voff) do { _Pragma("unroll") for (int _i = 0; _i < 2; ++_i) \
;         __builtin_amdgcn_global_load_lds((const unsigned*)((const char*)(gbase) + (voff)[_i]), (PG8_LAS unsigned*)(lds + (bufoff) + ldsw + _i * 8192), 16, 0, 0); } while (0)
; #define PG8_LDA(dst, b, h) do { _Pragma("unroll") for (int m = 0; m < 4; ++m) _Pragma("unroll") for (int k = 0; k < 2; ++k) dst[m][k] = *(const PG8_LAS bf16x8*)(lds + PG8_SA(b, h) + aoff + m * 2048 + k * 1024); } while (0)
; #define PG8_LDB(dst, b, h) do { _Pragma("unroll") for (int n = 0; n < 2; ++n) _Pragma("unroll") for (int k = 0; k < 2; ++k) dst[n][k] = *(const PG8_LAS bf16x8*)(lds + PG8_SB(b, h) + boff + n * 2048 + k * 1024); } while (0)
; #define PG8_MMA(ai, bj, At, Bt) do { __builtin_amdgcn_s_setprio(1); _Pragma("unroll") for (int m = 0; m < 4; ++m) _Pragma("unroll") for (int n = 0; n < 2; ++n) _Pragma("unroll") for (int k = 0; k < 2; ++k) \
;         acc[ai][bj][m][n] = __builtin_amdgcn_mfma_f32_16x16x32_bf16(Bt[n][k], At[m][k], acc[ai][bj][m][n], 0, 0, 0); __builtin_amdgcn_s_setprio(0); } while (0)
; #define PG8_WAIT_V(n) asm volatile("s_waitcnt vmcnt(" #n ")" ::: "memory")
; #define PG8_WAIT_L(n) asm volatile("s_waitcnt lgkmcnt(" #n ")" ::: "memory")
; template <class Epi, class Sched, bool ALIGN_EPI = false, bool SP2 = false>
; __device__ __forceinline__ void gemm_phase(PG8_LAS unsigned char* lds, const Gemm g, const Sched& S, const Epi& E) {
;     ...
;             const bool last = (t == nt - 2);
;             const char* a1 = cA + (size_t)(t + 1) * kstep;
;             const char* a2 = last ? nA : cA + (size_t)(t + 2) * kstep; const char* b2 = last ? nB : cB + (size_t)(t + 2) * kstep;
;             const char* a3 = a2 + kstep; const char* b3 = b2 + kstep;
;             if (last && has_next) S.a_ready(nxt);
;             if constexpr (SP2) {
;             PG8_LDB(B0, 0, 0); PG8_LDB(B1, 0, 1); PG8_SCHED; PG8_LDA(At, 0, 0); PG8_STAGE(PG8_SA(1, 1), a1 + hstep, voffA);
;             PG8_WAIT_V(8); PG8_WAIT_L(0); PG8_BAR; PG8_MMA(0, 0, At, B0); PG8_MMA(0, 1, At, B1); PG8_BAR; PG8_SCHED;
;             PG8_LDA(At, 0, 1); PG8_STAGE(PG8_SB(0, 0), b2, voffB); PG8_STAGE(PG8_SB(0, 1), b2 + hstep, voffB); PG8_STAGE(PG8_SA(0, 0), a2, voffA);
;             PG8_WAIT_V(8); PG8_WAIT_L(0); PG8_BAR; PG8_MMA(1, 0, At, B0); PG8_MMA(1, 1, At, B1); PG8_BAR; PG8_SCHED;
.LBB0_164:
	s_ashr_i32 s47, s46, 31
	s_lshl_b64 s[58:59], s[46:47], 20
	s_add_u32 s74, s12, s58
	s_addc_u32 s75, s13, s59
	s_and_b64 s[58:59], s[40:41], exec
	s_cselect_b32 s47, s75, s43
	s_cselect_b32 s55, s74, s42
	s_ashr_i32 s45, s44, 31
	s_lshl_b64 s[58:59], s[44:45], 20
	v_readlane_b32 s68, v255, 52
	v_readlane_b32 s69, v255, 53
	s_add_u32 s76, s68, s58
	s_addc_u32 s77, s69, s59
	s_and_b64 s[58:59], s[40:41], exec
	s_cselect_b32 s45, s77, s79
	s_cselect_b32 s58, s76, s78
	s_add_u32 s42, s42, 0x80080
	s_addc_u32 s43, s43, 0
	s_add_u32 s59, s78, 0x100
	v_mov_b32_e32 v0, 0
	s_addc_u32 s63, s79, 0
	s_mov_b32 s71, -2
	s_waitcnt vmcnt(0)
	s_add_u32 s68, s42, 0xfff80080
	s_addc_u32 s69, s43, -1
	s_add_i32 s82, 0, 0x10000
	s_cmp_eq_u32 s71, 28
	s_cselect_b32 s81, s47, s69
	s_cselect_b32 s80, s55, s68
	v_add_u32_e32 v144, s82, v147
	s_cselect_b32 s79, s45, s63
	s_cselect_b32 s78, s58, s59
	s_add_i32 s83, 0, 0x14000
	ds_read_b128 v[140:143], v144
	ds_read_b128 v[156:159], v144 offset:1024
	ds_read_b128 v[160:163], v144 offset:2048
	ds_read_b128 v[164:167], v144 offset:3072
	v_add_u32_e32 v144, s83, v147
	ds_read_b128 v[168:171], v144
	ds_read_b128 v[172:175], v144 offset:1024
	ds_read_b128 v[192:195], v144 offset:2048
	ds_read_b128 v[196:199], v144 offset:3072
	v_lshl_add_u64 v[150:151], s[42:43], 0, v[136:137]
	s_add_i32 m0, s14, 0xc000
	ds_read_b128 v[200:203], v149
	ds_read_b128 v[204:207], v149 offset:1024
	ds_read_b128 v[208:211], v149 offset:2048
	ds_read_b128 v[212:215], v149 offset:3072
	ds_read_b128 v[216:219], v149 offset:4096
	ds_read_b128 v[220:223], v149 offset:5120
	ds_read_b128 v[224:227], v149 offset:6144
	ds_read_b128 v[228:231], v149 offset:7168
	global_load_lds_dwordx4 v[150:151], off
	v_lshl_add_u64 v[150:151], s[42:43], 0, v[138:139]
	s_add_i32 m0, s14, 0xe000
	s_nop 0
	global_load_lds_dwordx4 v[150:151], off
	s_waitcnt vmcnt(8)
	s_waitcnt lgkmcnt(0)
	s_setprio 1
	s_barrier
	v_mfma_f32_16x16x32_bf16 v[124:127], v[140:143], v[200:203], 0
	v_mfma_f32_16x16x32_bf16 v[120:123], v[160:163], v[200:203], 0
	v_mfma_f32_16x16x32_bf16 v[108:111], v[140:143], v[208:211], 0
	v_mfma_f32_16x16x32_bf16 v[104:107], v[160:163], v[208:211], 0
	v_mfma_f32_16x16x32_bf16 v[92:95], v[140:143], v[216:219], 0
	v_mfma_f32_16x16x32_bf16 v[88:91], v[160:163], v[216:219], 0
	v_mfma_f32_16x16x32_bf16 v[76:79], v[140:143], v[224:227], 0
	v_mfma_f32_16x16x32_bf16 v[72:75], v[160:163], v[224:227], 0
	v_mfma_f32_16x16x32_bf16 v[124:127], v[156:159], v[204:207], v[124:127]
	v_mfma_f32_16x16x32_bf16 v[120:123], v[164:167], v[204:207], v[120:123]
	v_mfma_f32_16x16x32_bf16 v[108:111], v[156:159], v[212:215], v[108:111]
	v_mfma_f32_16x16x32_bf16 v[104:107], v[164:167], v[212:215], v[104:107]
	v_mfma_f32_16x16x32_bf16 v[92:95], v[156:159], v[220:223], v[92:95]
	v_mfma_f32_16x16x32_bf16 v[88:91], v[164:167], v[220:223], v[88:91]
	v_mfma_f32_16x16x32_bf16 v[76:79], v[156:159], v[228:231], v[76:79]
	v_mfma_f32_16x16x32_bf16 v[72:75], v[164:167], v[228:231], v[72:75]
	v_mfma_f32_16x16x32_bf16 v[116:119], v[168:171], v[200:203], 0
	v_mfma_f32_16x16x32_bf16 v[112:115], v[192:195], v[200:203], 0
	v_mfma_f32_16x16x32_bf16 v[100:103], v[168:171], v[208:211], 0
	v_mfma_f32_16x16x32_bf16 v[96:99], v[192:195], v[208:211], 0
	v_mfma_f32_16x16x32_bf16 v[84:87], v[168:171], v[216:219], 0
	v_mfma_f32_16x16x32_bf16 v[80:83], v[192:195], v[216:219], 0
	v_mfma_f32_16x16x32_bf16 v[68:71], v[168:171], v[224:227], 0
	v_mfma_f32_16x16x32_bf16 v[64:67], v[192:195], v[224:227], 0
	v_mfma_f32_16x16x32_bf16 v[116:119], v[172:175], v[204:207], v[116:119]
	v_mfma_f32_16x16x32_bf16 v[112:115], v[196:199], v[204:207], v[112:115]
	v_mfma_f32_16x16x32_bf16 v[100:103], v[172:175], v[212:215], v[100:103]
	v_mfma_f32_16x16x32_bf16 v[96:99], v[196:199], v[212:215], v[96:99]
	v_mfma_f32_16x16x32_bf16 v[84:87], v[172:175], v[220:223], v[84:87]
	v_mfma_f32_16x16x32_bf16 v[80:83], v[196:199], v[220:223], v[80:83]
	v_mfma_f32_16x16x32_bf16 v[68:71], v[172:175], v[228:231], v[68:71]
	v_mfma_f32_16x16x32_bf16 v[64:67], v[196:199], v[228:231], v[64:67]
	s_barrier
	s_setprio 0
	s_add_i32 s68, s82, s0
	v_lshl_add_u64 v[150:151], s[78:79], 0, v[152:153]
	s_mov_b32 m0, s68
	ds_read_b128 v[200:203], v149 offset:16384
	ds_read_b128 v[204:207], v149 offset:17408
	ds_read_b128 v[208:211], v149 offset:18432
	ds_read_b128 v[212:215], v149 offset:19456
	ds_read_b128 v[216:219], v149 offset:20480
	ds_read_b128 v[220:223], v149 offset:21504
	ds_read_b128 v[224:227], v149 offset:22528
	ds_read_b128 v[228:231], v149 offset:23552
	global_load_lds_dwordx4 v[150:151], off
	s_add_i32 m0, s68, 0x2000
	s_add_u32 s68, s78, 0x80000
	v_lshl_add_u64 v[182:183], s[78:79], 0, v[128:129]
	s_addc_u32 s69, s79, 0
	s_add_i32 s82, s83, s0
	global_load_lds_dwordx4 v[182:183], off
	v_lshl_add_u64 v[184:185], s[68:69], 0, v[152:153]
	s_mov_b32 m0, s82
	v_lshl_add_u64 v[188:189], s[80:81], 0, v[130:131]
	global_load_lds_dwordx4 v[184:185], off
	v_lshl_add_u64 v[184:185], s[68:69], 0, v[128:129]
	s_add_i32 m0, s82, 0x2000
	s_nop 0
	global_load_lds_dwordx4 v[184:185], off
	v_lshl_add_u64 v[184:185], s[80:81], 0, v[132:133]
	s_mov_b32 m0, s14
	s_nop 0
	global_load_lds_dwordx4 v[184:185], off
	s_mov_b32 m0, s15
	s_nop 0
	global_load_lds_dwordx4 v[188:189], off
	s_waitcnt vmcnt(8)
	s_waitcnt lgkmcnt(0)
	s_setprio 1
	s_barrier
; #define PG8_STAGE(bufoff, gbase, voff) do { _Pragma("unroll") for (int _i = 0; _i < 2; ++_i) \
;         __builtin_amdgcn_global_load_lds((const unsigned*)((const char*)(gbase) + (voff)[_i]), (PG8_LAS unsigned*)(lds + (bufoff) + ldsw + _i * 8192), 16, 0, 0); } while (0)
; #define PG8_LDA(dst, b, h) do { _Pragma("unroll") for (int m = 0; m < 4; ++m) _Pragma("unroll") for (int k = 0; k < 2; ++k) dst[m][k] = *(const PG8_LAS bf16x8*)(lds + PG8_SA(b, h) + aoff + m * 2048 + k * 1024); } while (0)
; #define PG8_LDB(dst, b, h) do { _Pragma("unroll") for (int n = 0; n < 2; ++n) _Pragma("unroll") for (int k = 0; k < 2; ++k) dst[n][k] = *(const PG8_LAS bf16x8*)(lds + PG8_SB(b, h) + boff + n * 2048 + k * 1024); } while (0)
; #define PG8_MMA(ai, bj, At, Bt) do { __builtin_amdgcn_s_setprio(1); _Pragma("unroll") for (int m = 0; m < 4; ++m) _Pragma("unroll") for (int n = 0; n < 2; ++n) _Pragma("unroll") for (int k = 0; k < 2; ++k) \
;         acc[ai][bj][m][n] = __builtin_amdgcn_mfma_f32_16x16x32_bf16(Bt[n][k], At[m][k], acc[ai][bj][m][n], 0, 0, 0); __builtin_amdgcn_s_setprio(0); } while (0)
; #define PG8_WAIT_V(n) asm volatile("s_waitcnt vmcnt(" #n ")" ::: "memory")
; #define PG8_WAIT_L(n) asm volatile("s_waitcnt lgkmcnt(" #n ")" ::: "memory")
; #define PG8_BAR __builtin_amdgcn_s_barrier()
; #define PG8_SCHED __builtin_amdgcn_sched_barrier(0)
; template <class Epi, class Sched, bool ALIGN_EPI = false, bool SP2 = false>
; __device__ __forceinline__ void gemm_phase(PG8_LAS unsigned char* lds, const Gemm g, const Sched& S, const Epi& E) {
;     ...
;             PG8_WAIT_V(8); PG8_WAIT_L(0); PG8_BAR; PG8_MMA(1, 0, At, B0); PG8_MMA(1, 1, At, B1); PG8_BAR; PG8_SCHED;
;             PG8_LDB(B0, 1, 0); PG8_LDB(B1, 1, 1); PG8_SCHED; PG8_LDA(At, 1, 0); PG8_STAGE(PG8_SA(0, 1), a2 + hstep, voffA);
;             PG8_WAIT_V(8); PG8_WAIT_L(0); PG8_BAR; PG8_MMA(0, 0, At, B0); PG8_MMA(0, 1, At, B1); PG8_BAR; PG8_SCHED;
;             PG8_LDA(At, 1, 1); PG8_STAGE(PG8_SB(1, 0), b3, voffB); PG8_STAGE(PG8_SB(1, 1), b3 + hstep, voffB); PG8_STAGE(PG8_SA(1, 0), a3, voffA);
	v_mfma_f32_16x16x32_bf16 v[60:63], v[140:143], v[200:203], 0
	v_mfma_f32_16x16x32_bf16 v[56:59], v[160:163], v[200:203], 0
	v_mfma_f32_16x16x32_bf16 v[44:47], v[140:143], v[208:211], 0
	v_mfma_f32_16x16x32_bf16 v[40:43], v[160:163], v[208:211], 0
	v_mfma_f32_16x16x32_bf16 v[28:31], v[140:143], v[216:219], 0
	v_mfma_f32_16x16x32_bf16 v[24:27], v[160:163], v[216:219], 0
	v_mfma_f32_16x16x32_bf16 v[12:15], v[140:143], v[224:227], 0
	v_mfma_f32_16x16x32_bf16 v[8:11], v[160:163], v[224:227], 0
	v_mfma_f32_16x16x32_bf16 v[60:63], v[156:159], v[204:207], v[60:63]
	v_mfma_f32_16x16x32_bf16 v[56:59], v[164:167], v[204:207], v[56:59]
	v_mfma_f32_16x16x32_bf16 v[44:47], v[156:159], v[212:215], v[44:47]
	v_mfma_f32_16x16x32_bf16 v[40:43], v[164:167], v[212:215], v[40:43]
	v_mfma_f32_16x16x32_bf16 v[28:31], v[156:159], v[220:223], v[28:31]
	v_mfma_f32_16x16x32_bf16 v[24:27], v[164:167], v[220:223], v[24:27]
	v_mfma_f32_16x16x32_bf16 v[12:15], v[156:159], v[228:231], v[12:15]
	v_mfma_f32_16x16x32_bf16 v[8:11], v[164:167], v[228:231], v[8:11]
	v_mfma_f32_16x16x32_bf16 v[52:55], v[168:171], v[200:203], 0
	v_mfma_f32_16x16x32_bf16 v[48:51], v[192:195], v[200:203], 0
	v_mfma_f32_16x16x32_bf16 v[36:39], v[168:171], v[208:211], 0
	v_mfma_f32_16x16x32_bf16 v[32:35], v[192:195], v[208:211], 0
	v_mfma_f32_16x16x32_bf16 v[20:23], v[168:171], v[216:219], 0
	v_mfma_f32_16x16x32_bf16 v[16:19], v[192:195], v[216:219], 0
	v_mfma_f32_16x16x32_bf16 v[4:7], v[168:171], v[224:227], 0
	v_mfma_f32_16x16x32_bf16 v[0:3], v[192:195], v[224:227], 0
	v_mfma_f32_16x16x32_bf16 v[52:55], v[172:175], v[204:207], v[52:55]
	v_mfma_f32_16x16x32_bf16 v[48:51], v[196:199], v[204:207], v[48:51]
	v_mfma_f32_16x16x32_bf16 v[36:39], v[172:175], v[212:215], v[36:39]
	v_mfma_f32_16x16x32_bf16 v[32:35], v[196:199], v[212:215], v[32:35]
	v_mfma_f32_16x16x32_bf16 v[20:23], v[172:175], v[220:223], v[20:23]
	v_mfma_f32_16x16x32_bf16 v[16:19], v[196:199], v[220:223], v[16:19]
	v_mfma_f32_16x16x32_bf16 v[4:7], v[172:175], v[228:231], v[4:7]
	v_mfma_f32_16x16x32_bf16 v[0:3], v[196:199], v[228:231], v[0:3]
	s_barrier
	s_setprio 0
	v_add_u32_e32 v144, s93, v147
	s_add_i32 s82, 0, 0x1c000
	ds_read_b128 v[140:143], v144
	ds_read_b128 v[156:159], v144 offset:1024
	ds_read_b128 v[160:163], v144 offset:2048
	ds_read_b128 v[164:167], v144 offset:3072
	v_add_u32_e32 v144, s82, v147
	ds_read_b128 v[168:171], v144
	ds_read_b128 v[172:175], v144 offset:1024
	ds_read_b128 v[192:195], v144 offset:2048
	ds_read_b128 v[196:199], v144 offset:3072
	s_add_u32 s68, s80, 0x80000
	s_addc_u32 s69, s81, 0
	s_mov_b32 m0, s16
	v_lshl_add_u64 v[190:191], s[68:69], 0, v[132:133]
	ds_read_b128 v[200:203], v149 offset:32768
	ds_read_b128 v[204:207], v149 offset:33792
	ds_read_b128 v[208:211], v149 offset:34816
	ds_read_b128 v[212:215], v149 offset:35840
	ds_read_b128 v[216:219], v149 offset:36864
	ds_read_b128 v[220:223], v149 offset:37888
	ds_read_b128 v[224:227], v149 offset:38912
	ds_read_b128 v[228:231], v149 offset:39936
	global_load_lds_dwordx4 v[190:191], off
	v_lshl_add_u64 v[190:191], s[68:69], 0, v[130:131]
	s_mov_b32 m0, s17
	s_nop 0
	global_load_lds_dwordx4 v[190:191], off
	s_waitcnt vmcnt(8)
	s_waitcnt lgkmcnt(0)
	s_setprio 1
	s_barrier
	v_mfma_f32_16x16x32_bf16 v[124:127], v[140:143], v[200:203], v[124:127]
	v_mfma_f32_16x16x32_bf16 v[120:123], v[160:163], v[200:203], v[120:123]
	v_mfma_f32_16x16x32_bf16 v[108:111], v[140:143], v[208:211], v[108:111]
	v_mfma_f32_16x16x32_bf16 v[104:107], v[160:163], v[208:211], v[104:107]
	v_mfma_f32_16x16x32_bf16 v[92:95], v[140:143], v[216:219], v[92:95]
	v_mfma_f32_16x16x32_bf16 v[88:91], v[160:163], v[216:219], v[88:91]
	v_mfma_f32_16x16x32_bf16 v[76:79], v[140:143], v[224:227], v[76:79]
	v_mfma_f32_16x16x32_bf16 v[72:75], v[160:163], v[224:227], v[72:75]
	v_mfma_f32_16x16x32_bf16 v[124:127], v[156:159], v[204:207], v[124:127]
	v_mfma_f32_16x16x32_bf16 v[120:123], v[164:167], v[204:207], v[120:123]
	v_mfma_f32_16x16x32_bf16 v[108:111], v[156:159], v[212:215], v[108:111]
	v_mfma_f32_16x16x32_bf16 v[104:107], v[164:167], v[212:215], v[104:107]
	v_mfma_f32_16x16x32_bf16 v[92:95], v[156:159], v[220:223], v[92:95]
	v_mfma_f32_16x16x32_bf16 v[88:91], v[164:167], v[220:223], v[88:91]
	v_mfma_f32_16x16x32_bf16 v[76:79], v[156:159], v[228:231], v[76:79]
	v_mfma_f32_16x16x32_bf16 v[72:75], v[164:167], v[228:231], v[72:75]
	v_mfma_f32_16x16x32_bf16 v[116:119], v[168:171], v[200:203], v[116:119]
	v_mfma_f32_16x16x32_bf16 v[112:115], v[192:195], v[200:203], v[112:115]
	v_mfma_f32_16x16x32_bf16 v[100:103], v[168:171], v[208:211], v[100:103]
	v_mfma_f32_16x16x32_bf16 v[96:99], v[192:195], v[208:211], v[96:99]
	v_mfma_f32_16x16x32_bf16 v[84:87], v[168:171], v[216:219], v[84:87]
	v_mfma_f32_16x16x32_bf16 v[80:83], v[192:195], v[216:219], v[80:83]
	v_mfma_f32_16x16x32_bf16 v[68:71], v[168:171], v[224:227], v[68:71]
	v_mfma_f32_16x16x32_bf16 v[64:67], v[192:195], v[224:227], v[64:67]
	v_mfma_f32_16x16x32_bf16 v[116:119], v[172:175], v[204:207], v[116:119]
	v_mfma_f32_16x16x32_bf16 v[112:115], v[196:199], v[204:207], v[112:115]
	v_mfma_f32_16x16x32_bf16 v[100:103], v[172:175], v[212:215], v[100:103]
	v_mfma_f32_16x16x32_bf16 v[96:99], v[196:199], v[212:215], v[96:99]
	v_mfma_f32_16x16x32_bf16 v[84:87], v[172:175], v[220:223], v[84:87]
	v_mfma_f32_16x16x32_bf16 v[80:83], v[196:199], v[220:223], v[80:83]
	v_mfma_f32_16x16x32_bf16 v[68:71], v[172:175], v[228:231], v[68:71]
	v_mfma_f32_16x16x32_bf16 v[64:67], v[196:199], v[228:231], v[64:67]
	s_barrier
; #define PG8_STAGE(bufoff, gbase, voff) do { _Pragma("unroll") for (int _i = 0; _i < 2; ++_i) \
;         __builtin_amdgcn_global_load_lds((const unsigned*)((const char*)(gbase) + (voff)[_i]), (PG8_LAS unsigned*)(lds + (bufoff) + ldsw + _i * 8192), 16, 0, 0); } while (0)
; #define PG8_LDA(dst, b, h) do { _Pragma("unroll") for (int m = 0; m < 4; ++m) _Pragma("unroll") for (int k = 0; k < 2; ++k) dst[m][k] = *(const PG8_LAS bf16x8*)(lds + PG8_SA(b, h) + aoff + m * 2048 + k * 1024); } while (0)
; #define PG8_MMA(ai, bj, At, Bt) do { __builtin_amdgcn_s_setprio(1); _Pragma("unroll") for (int m = 0; m < 4; ++m) _Pragma("unroll") for (int n = 0; n < 2; ++n) _Pragma("unroll") for (int k = 0; k < 2; ++k) \
;         acc[ai][bj][m][n] = __builtin_amdgcn_mfma_f32_16x16x32_bf16(Bt[n][k], At[m][k], acc[ai][bj][m][n], 0, 0, 0); __builtin_amdgcn_s_setprio(0); } while (0)
; #define PG8_WAIT_V(n) asm volatile("s_waitcnt vmcnt(" #n ")" ::: "memory")
; #define PG8_WAIT_L(n) asm volatile("s_waitcnt lgkmcnt(" #n ")" ::: "memory")
; #define PG8_BAR __builtin_amdgcn_s_barrier()
; #define PG8_SCHED __builtin_amdgcn_sched_barrier(0)
; template <class Epi, class Sched, bool ALIGN_EPI = false, bool SP2 = false>
; __device__ __forceinline__ void gemm_phase(PG8_LAS unsigned char* lds, const Gemm g, const Sched& S, const Epi& E) {
;     ...
;             PG8_LDA(At, 1, 1); PG8_STAGE(PG8_SB(1, 0), b3, voffB); PG8_STAGE(PG8_SB(1, 1), b3 + hstep, voffB); PG8_STAGE(PG8_SA(1, 0), a3, voffA);
;             PG8_WAIT_V(8); PG8_WAIT_L(0); PG8_BAR; PG8_MMA(1, 0, At, B0); PG8_MMA(1, 1, At, B1); PG8_BAR; PG8_SCHED;
	s_setprio 0
	s_add_i32 s68, s93, s0
	v_lshl_add_u64 v[150:151], v[150:151], 0, s[18:19]
	s_mov_b32 m0, s68
	ds_read_b128 v[200:203], v149 offset:49152
	ds_read_b128 v[204:207], v149 offset:50176
	ds_read_b128 v[208:211], v149 offset:51200
	ds_read_b128 v[212:215], v149 offset:52224
	ds_read_b128 v[216:219], v149 offset:53248
	ds_read_b128 v[220:223], v149 offset:54272
	ds_read_b128 v[224:227], v149 offset:55296
	ds_read_b128 v[228:231], v149 offset:56320
	global_load_lds_dwordx4 v[150:151], off
	s_add_i32 m0, s68, 0x2000
	s_add_u32 s68, s78, 0x80080
	v_lshl_add_u64 v[150:151], v[182:183], 0, s[18:19]
	s_addc_u32 s69, s79, 0
	s_add_i32 s78, s82, s0
	global_load_lds_dwordx4 v[150:151], off
	v_lshl_add_u64 v[150:151], s[68:69], 0, v[152:153]
	s_mov_b32 m0, s78
	s_nop 0
	global_load_lds_dwordx4 v[150:151], off
	v_lshl_add_u64 v[150:151], s[68:69], 0, v[128:129]
	s_add_i32 m0, s78, 0x2000
	s_nop 0
	global_load_lds_dwordx4 v[150:151], off
	v_lshl_add_u64 v[150:151], v[184:185], 0, s[18:19]
	s_mov_b32 m0, s22
	s_nop 0
	global_load_lds_dwordx4 v[150:151], off
	v_lshl_add_u64 v[150:151], v[188:189], 0, s[18:19]
	s_mov_b32 m0, s23
	s_nop 0
	global_load_lds_dwordx4 v[150:151], off
	s_waitcnt vmcnt(8)
	s_waitcnt lgkmcnt(0)
	s_setprio 1
	s_barrier
	v_mfma_f32_16x16x32_bf16 v[60:63], v[140:143], v[200:203], v[60:63]
	v_mfma_f32_16x16x32_bf16 v[56:59], v[160:163], v[200:203], v[56:59]
	v_mfma_f32_16x16x32_bf16 v[44:47], v[140:143], v[208:211], v[44:47]
	v_mfma_f32_16x16x32_bf16 v[40:43], v[160:163], v[208:211], v[40:43]
	v_mfma_f32_16x16x32_bf16 v[28:31], v[140:143], v[216:219], v[28:31]
	v_mfma_f32_16x16x32_bf16 v[24:27], v[160:163], v[216:219], v[24:27]
	v_mfma_f32_16x16x32_bf16 v[12:15], v[140:143], v[224:227], v[12:15]
	v_mfma_f32_16x16x32_bf16 v[8:11], v[160:163], v[224:227], v[8:11]
	v_mfma_f32_16x16x32_bf16 v[60:63], v[156:159], v[204:207], v[60:63]
	v_mfma_f32_16x16x32_bf16 v[56:59], v[164:167], v[204:207], v[56:59]
	v_mfma_f32_16x16x32_bf16 v[44:47], v[156:159], v[212:215], v[44:47]
	v_mfma_f32_16x16x32_bf16 v[40:43], v[164:167], v[212:215], v[40:43]
	v_mfma_f32_16x16x32_bf16 v[28:31], v[156:159], v[220:223], v[28:31]
	v_mfma_f32_16x16x32_bf16 v[24:27], v[164:167], v[220:223], v[24:27]
	v_mfma_f32_16x16x32_bf16 v[12:15], v[156:159], v[228:231], v[12:15]
	v_mfma_f32_16x16x32_bf16 v[8:11], v[164:167], v[228:231], v[8:11]
	v_mfma_f32_16x16x32_bf16 v[52:55], v[168:171], v[200:203], v[52:55]
	v_mfma_f32_16x16x32_bf16 v[48:51], v[192:195], v[200:203], v[48:51]
	v_mfma_f32_16x16x32_bf16 v[36:39], v[168:171], v[208:211], v[36:39]
	v_mfma_f32_16x16x32_bf16 v[32:35], v[192:195], v[208:211], v[32:35]
	v_mfma_f32_16x16x32_bf16 v[20:23], v[168:171], v[216:219], v[20:23]
	v_mfma_f32_16x16x32_bf16 v[16:19], v[192:195], v[216:219], v[16:19]
	v_mfma_f32_16x16x32_bf16 v[4:7], v[168:171], v[224:227], v[4:7]
	v_mfma_f32_16x16x32_bf16 v[0:3], v[192:195], v[224:227], v[0:3]
	v_mfma_f32_16x16x32_bf16 v[52:55], v[172:175], v[204:207], v[52:55]
	v_mfma_f32_16x16x32_bf16 v[48:51], v[196:199], v[204:207], v[48:51]
	v_mfma_f32_16x16x32_bf16 v[36:39], v[172:175], v[212:215], v[36:39]
	v_mfma_f32_16x16x32_bf16 v[32:35], v[196:199], v[212:215], v[32:35]
	v_mfma_f32_16x16x32_bf16 v[20:23], v[172:175], v[220:223], v[20:23]
	v_mfma_f32_16x16x32_bf16 v[16:19], v[196:199], v[220:223], v[16:19]
	v_mfma_f32_16x16x32_bf16 v[4:7], v[172:175], v[228:231], v[4:7]
	v_mfma_f32_16x16x32_bf16 v[0:3], v[196:199], v[228:231], v[0:3]
	s_barrier
	s_setprio 0
	s_add_i32 s71, s71, 2
	s_add_u32 s42, s42, 0x100
	s_addc_u32 s43, s43, 0
	s_add_u32 s59, s59, 0x100
	s_addc_u32 s63, s63, 0
	s_cmp_gt_u32 s71, 29
	s_cbranch_scc1 .Lpeel_exit_165

; #define PG8_STAGE(bufoff, gbase, voff) do { _Pragma("unroll") for (int _i = 0; _i < 2; ++_i) \
;         __builtin_amdgcn_global_load_lds((const unsigned*)((const char*)(gbase) + (voff)[_i]), (PG8_LAS unsigned*)(lds + (bufoff) + ldsw + _i * 8192), 16, 0, 0); } while (0)
; #define PG8_LDA(dst, b, h) do { _Pragma("unroll") for (int m = 0; m < 4; ++m) _Pragma("unroll") for (int k = 0; k < 2; ++k) dst[m][k] = *(const PG8_LAS bf16x8*)(lds + PG8_SA(b, h) + aoff + m * 2048 + k * 1024); } while (0)
; #define PG8_LDB(dst, b, h) do { _Pragma("unroll") for (int n = 0; n < 2; ++n) _Pragma("unroll") for (int k = 0; k < 2; ++k) dst[n][k] = *(const PG8_LAS bf16x8*)(lds + PG8_SB(b, h) + boff + n * 2048 + k * 1024); } while (0)
; #define PG8_MMA(ai, bj, At, Bt) do { __builtin_amdgcn_s_setprio(1); _Pragma("unroll") for (int m = 0; m < 4; ++m) _Pragma("unroll") for (int n = 0; n < 2; ++n) _Pragma("unroll") for (int k = 0; k < 2; ++k) \
;         acc[ai][bj][m][n] = __builtin_amdgcn_mfma_f32_16x16x32_bf16(Bt[n][k], At[m][k], acc[ai][bj][m][n], 0, 0, 0); __builtin_amdgcn_s_setprio(0); } while (0)
; #define PG8_WAIT_V(n) asm volatile("s_waitcnt vmcnt(" #n ")" ::: "memory")
; #define PG8_WAIT_L(n) asm volatile("s_waitcnt lgkmcnt(" #n ")" ::: "memory")
; template <class Epi, class Sched, bool ALIGN_EPI = false, bool SP2 = false>
; __device__ __forceinline__ void gemm_phase(PG8_LAS unsigned char* lds, const Gemm g, const Sched& S, const Epi& E) {
;     ...
;             const bool last = (t == nt - 2);
;             const char* a1 = cA + (size_t)(t + 1) * kstep;
;             const char* a2 = last ? nA : cA + (size_t)(t + 2) * kstep; const char* b2 = last ? nB : cB + (size_t)(t + 2) * kstep;
;             const char* a3 = a2 + kstep; const char* b3 = b2 + kstep;
;             if (last && has_next) S.a_ready(nxt);
;             if constexpr (SP2) {
;             PG8_LDB(B0, 0, 0); PG8_LDB(B1, 0, 1); PG8_SCHED; PG8_LDA(At, 0, 0); PG8_STAGE(PG8_SA(1, 1), a1 + hstep, voffA);
;             PG8_WAIT_V(8); PG8_WAIT_L(0); PG8_BAR; PG8_MMA(0, 0, At, B0); PG8_MMA(0, 1, At, B1); PG8_BAR; PG8_SCHED;
;             PG8_LDA(At, 0, 1); PG8_STAGE(PG8_SB(0, 0), b2, voffB); PG8_STAGE(PG8_SB(0, 1), b2 + hstep, voffB); PG8_STAGE(PG8_SA(0, 0), a2, voffA);
;             PG8_WAIT_V(8); PG8_WAIT_L(0); PG8_BAR; PG8_MMA(1, 0, At, B0); PG8_MMA(1, 1, At, B1); PG8_BAR; PG8_SCHED;
.LBB0_217:
	s_add_u32 s44, s86, 0x80
	s_addc_u32 s45, s87, 0
	s_add_u32 s86, s46, 0x100
	v_mov_b32_e32 v0, 0
	s_addc_u32 s87, s47, 0
	s_mov_b32 s46, 0
	s_waitcnt vmcnt(0)
	s_add_i32 vcc_lo, s46, 2
	s_add_u32 s68, s44, 0x80
	s_addc_u32 s47, s45, 0
	s_add_i32 vcc_hi, 0, 0x10000
	s_cmp_eq_u32 s15, s46
	s_cselect_b32 s47, s83, s47
	s_cselect_b32 s46, s82, s68
	v_add_u32_e32 v146, vcc_hi, v149
	s_cselect_b32 s69, s85, s87
	s_cselect_b32 s68, s84, s86
	s_add_i32 s96, 0, 0x14000
	ds_read_b128 v[138:141], v146
	ds_read_b128 v[142:145], v146 offset:1024
	ds_read_b128 v[156:159], v146 offset:2048
	ds_read_b128 v[160:163], v146 offset:3072
	v_add_u32_e32 v146, s96, v149
	ds_read_b128 v[164:167], v146
	ds_read_b128 v[168:171], v146 offset:1024
	ds_read_b128 v[172:175], v146 offset:2048
	ds_read_b128 v[192:195], v146 offset:3072
	v_lshl_add_u64 v[146:147], s[44:45], 0, v[134:135]
	s_add_i32 m0, s54, 0xc000
	ds_read_b128 v[196:199], v151
	ds_read_b128 v[200:203], v151 offset:1024
	ds_read_b128 v[204:207], v151 offset:2048
	ds_read_b128 v[208:211], v151 offset:3072
	ds_read_b128 v[212:215], v151 offset:4096
	ds_read_b128 v[216:219], v151 offset:5120
	ds_read_b128 v[220:223], v151 offset:6144
	ds_read_b128 v[224:227], v151 offset:7168
	global_load_lds_dwordx4 v[146:147], off
	v_lshl_add_u64 v[146:147], s[44:45], 0, v[136:137]
	s_add_i32 m0, s54, 0xe000
	s_nop 0
	global_load_lds_dwordx4 v[146:147], off
	s_waitcnt vmcnt(8)
	s_waitcnt lgkmcnt(0)
	s_setprio 1
	s_barrier
	v_mfma_f32_16x16x32_bf16 v[124:127], v[138:141], v[196:199], 0
	v_mfma_f32_16x16x32_bf16 v[120:123], v[156:159], v[196:199], 0
	v_mfma_f32_16x16x32_bf16 v[108:111], v[138:141], v[204:207], 0
	v_mfma_f32_16x16x32_bf16 v[104:107], v[156:159], v[204:207], 0
	v_mfma_f32_16x16x32_bf16 v[92:95], v[138:141], v[212:215], 0
	v_mfma_f32_16x16x32_bf16 v[88:91], v[156:159], v[212:215], 0
	v_mfma_f32_16x16x32_bf16 v[76:79], v[138:141], v[220:223], 0
	v_mfma_f32_16x16x32_bf16 v[72:75], v[156:159], v[220:223], 0
	v_mfma_f32_16x16x32_bf16 v[124:127], v[142:145], v[200:203], v[124:127]
	v_mfma_f32_16x16x32_bf16 v[120:123], v[160:163], v[200:203], v[120:123]
	v_mfma_f32_16x16x32_bf16 v[108:111], v[142:145], v[208:211], v[108:111]
	v_mfma_f32_16x16x32_bf16 v[104:107], v[160:163], v[208:211], v[104:107]
	v_mfma_f32_16x16x32_bf16 v[92:95], v[142:145], v[216:219], v[92:95]
	v_mfma_f32_16x16x32_bf16 v[88:91], v[160:163], v[216:219], v[88:91]
	v_mfma_f32_16x16x32_bf16 v[76:79], v[142:145], v[224:227], v[76:79]
	v_mfma_f32_16x16x32_bf16 v[72:75], v[160:163], v[224:227], v[72:75]
	v_mfma_f32_16x16x32_bf16 v[116:119], v[164:167], v[196:199], 0
	v_mfma_f32_16x16x32_bf16 v[112:115], v[172:175], v[196:199], 0
	v_mfma_f32_16x16x32_bf16 v[100:103], v[164:167], v[204:207], 0
	v_mfma_f32_16x16x32_bf16 v[96:99], v[172:175], v[204:207], 0
	v_mfma_f32_16x16x32_bf16 v[84:87], v[164:167], v[212:215], 0
	v_mfma_f32_16x16x32_bf16 v[80:83], v[172:175], v[212:215], 0
	v_mfma_f32_16x16x32_bf16 v[68:71], v[164:167], v[220:223], 0
	v_mfma_f32_16x16x32_bf16 v[64:67], v[172:175], v[220:223], 0
	v_mfma_f32_16x16x32_bf16 v[116:119], v[168:171], v[200:203], v[116:119]
	v_mfma_f32_16x16x32_bf16 v[112:115], v[192:195], v[200:203], v[112:115]
	v_mfma_f32_16x16x32_bf16 v[100:103], v[168:171], v[208:211], v[100:103]
	v_mfma_f32_16x16x32_bf16 v[96:99], v[192:195], v[208:211], v[96:99]
	v_mfma_f32_16x16x32_bf16 v[84:87], v[168:171], v[216:219], v[84:87]
	v_mfma_f32_16x16x32_bf16 v[80:83], v[192:195], v[216:219], v[80:83]
	v_mfma_f32_16x16x32_bf16 v[68:71], v[168:171], v[224:227], v[68:71]
	v_mfma_f32_16x16x32_bf16 v[64:67], v[192:195], v[224:227], v[64:67]
	s_barrier
	s_setprio 0
	s_add_i32 vcc_hi, vcc_hi, s63
	v_lshl_add_u64 v[146:147], s[68:69], 0, v[152:153]
	s_mov_b32 m0, vcc_hi
	ds_read_b128 v[196:199], v151 offset:16384
	ds_read_b128 v[200:203], v151 offset:17408
	ds_read_b128 v[204:207], v151 offset:18432
	ds_read_b128 v[208:211], v151 offset:19456
	ds_read_b128 v[212:215], v151 offset:20480
	ds_read_b128 v[216:219], v151 offset:21504
	ds_read_b128 v[220:223], v151 offset:22528
	ds_read_b128 v[224:227], v151 offset:23552
	global_load_lds_dwordx4 v[146:147], off
	s_add_i32 m0, vcc_hi, 0x2000
	v_lshl_add_u64 v[182:183], s[68:69], 0, v[128:129]
	s_add_u32 s68, s68, s48
	s_addc_u32 s69, s69, 0
	s_add_i32 s96, s96, s63
	global_load_lds_dwordx4 v[182:183], off
	v_lshl_add_u64 v[184:185], s[68:69], 0, v[152:153]
	s_mov_b32 m0, s96
	v_lshl_add_u64 v[188:189], s[68:69], 0, v[128:129]
	global_load_lds_dwordx4 v[184:185], off
	s_add_i32 m0, s96, 0x2000
	v_lshl_add_u64 v[190:191], s[46:47], 0, v[132:133]
	global_load_lds_dwordx4 v[188:189], off
	s_mov_b32 m0, s54
	v_lshl_add_u64 v[228:229], s[46:47], 0, v[130:131]
	global_load_lds_dwordx4 v[190:191], off
	s_mov_b32 m0, s55
	s_nop 0
	global_load_lds_dwordx4 v[228:229], off
	s_waitcnt vmcnt(8)
	s_waitcnt lgkmcnt(0)
	s_setprio 1
	s_barrier
; #define PG8_STAGE(bufoff, gbase, voff) do { _Pragma("unroll") for (int _i = 0; _i < 2; ++_i) \
;         __builtin_amdgcn_global_load_lds((const unsigned*)((const char*)(gbase) + (voff)[_i]), (PG8_LAS unsigned*)(lds + (bufoff) + ldsw + _i * 8192), 16, 0, 0); } while (0)
; #define PG8_LDA(dst, b, h) do { _Pragma("unroll") for (int m = 0; m < 4; ++m) _Pragma("unroll") for (int k = 0; k < 2; ++k) dst[m][k] = *(const PG8_LAS bf16x8*)(lds + PG8_SA(b, h) + aoff + m * 2048 + k * 1024); } while (0)
; #define PG8_LDB(dst, b, h) do { _Pragma("unroll") for (int n = 0; n < 2; ++n) _Pragma("unroll") for (int k = 0; k < 2; ++k) dst[n][k] = *(const PG8_LAS bf16x8*)(lds + PG8_SB(b, h) + boff + n * 2048 + k * 1024); } while (0)
; #define PG8_MMA(ai, bj, At, Bt) do { __builtin_amdgcn_s_setprio(1); _Pragma("unroll") for (int m = 0; m < 4; ++m) _Pragma("unroll") for (int n = 0; n < 2; ++n) _Pragma("unroll") for (int k = 0; k < 2; ++k) \
;         acc[ai][bj][m][n] = __builtin_amdgcn_mfma_f32_16x16x32_bf16(Bt[n][k], At[m][k], acc[ai][bj][m][n], 0, 0, 0); __builtin_amdgcn_s_setprio(0); } while (0)
; #define PG8_WAIT_V(n) asm volatile("s_waitcnt vmcnt(" #n ")" ::: "memory")
; #define PG8_WAIT_L(n) asm volatile("s_waitcnt lgkmcnt(" #n ")" ::: "memory")
; #define PG8_BAR __builtin_amdgcn_s_barrier()
; #define PG8_SCHED __builtin_amdgcn_sched_barrier(0)
; template <class Epi, class Sched, bool ALIGN_EPI = false, bool SP2 = false>
; __device__ __forceinline__ void gemm_phase(PG8_LAS unsigned char* lds, const Gemm g, const Sched& S, const Epi& E) {
;     ...
;             PG8_WAIT_V(8); PG8_WAIT_L(0); PG8_BAR; PG8_MMA(1, 0, At, B0); PG8_MMA(1, 1, At, B1); PG8_BAR; PG8_SCHED;
;             PG8_LDB(B0, 1, 0); PG8_LDB(B1, 1, 1); PG8_SCHED; PG8_LDA(At, 1, 0); PG8_STAGE(PG8_SA(0, 1), a2 + hstep, voffA);
;             PG8_WAIT_V(8); PG8_WAIT_L(0); PG8_BAR; PG8_MMA(0, 0, At, B0); PG8_MMA(0, 1, At, B1); PG8_BAR; PG8_SCHED;
;             PG8_LDA(At, 1, 1); PG8_STAGE(PG8_SB(1, 0), b3, voffB); PG8_STAGE(PG8_SB(1, 1), b3 + hstep, voffB); PG8_STAGE(PG8_SA(1, 0), a3, voffA);
	v_mfma_f32_16x16x32_bf16 v[60:63], v[138:141], v[196:199], 0
	v_mfma_f32_16x16x32_bf16 v[56:59], v[156:159], v[196:199], 0
	v_mfma_f32_16x16x32_bf16 v[44:47], v[138:141], v[204:207], 0
	v_mfma_f32_16x16x32_bf16 v[40:43], v[156:159], v[204:207], 0
	v_mfma_f32_16x16x32_bf16 v[28:31], v[138:141], v[212:215], 0
	v_mfma_f32_16x16x32_bf16 v[24:27], v[156:159], v[212:215], 0
	v_mfma_f32_16x16x32_bf16 v[12:15], v[138:141], v[220:223], 0
	v_mfma_f32_16x16x32_bf16 v[8:11], v[156:159], v[220:223], 0
	v_mfma_f32_16x16x32_bf16 v[60:63], v[142:145], v[200:203], v[60:63]
	v_mfma_f32_16x16x32_bf16 v[56:59], v[160:163], v[200:203], v[56:59]
	v_mfma_f32_16x16x32_bf16 v[44:47], v[142:145], v[208:211], v[44:47]
	v_mfma_f32_16x16x32_bf16 v[40:43], v[160:163], v[208:211], v[40:43]
	v_mfma_f32_16x16x32_bf16 v[28:31], v[142:145], v[216:219], v[28:31]
	v_mfma_f32_16x16x32_bf16 v[24:27], v[160:163], v[216:219], v[24:27]
	v_mfma_f32_16x16x32_bf16 v[12:15], v[142:145], v[224:227], v[12:15]
	v_mfma_f32_16x16x32_bf16 v[8:11], v[160:163], v[224:227], v[8:11]
	v_mfma_f32_16x16x32_bf16 v[52:55], v[164:167], v[196:199], 0
	v_mfma_f32_16x16x32_bf16 v[48:51], v[172:175], v[196:199], 0
	v_mfma_f32_16x16x32_bf16 v[36:39], v[164:167], v[204:207], 0
	v_mfma_f32_16x16x32_bf16 v[32:35], v[172:175], v[204:207], 0
	v_mfma_f32_16x16x32_bf16 v[20:23], v[164:167], v[212:215], 0
	v_mfma_f32_16x16x32_bf16 v[16:19], v[172:175], v[212:215], 0
	v_mfma_f32_16x16x32_bf16 v[4:7], v[164:167], v[220:223], 0
	v_mfma_f32_16x16x32_bf16 v[0:3], v[172:175], v[220:223], 0
	v_mfma_f32_16x16x32_bf16 v[52:55], v[168:171], v[200:203], v[52:55]
	v_mfma_f32_16x16x32_bf16 v[48:51], v[192:195], v[200:203], v[48:51]
	v_mfma_f32_16x16x32_bf16 v[36:39], v[168:171], v[208:211], v[36:39]
	v_mfma_f32_16x16x32_bf16 v[32:35], v[192:195], v[208:211], v[32:35]
	v_mfma_f32_16x16x32_bf16 v[20:23], v[168:171], v[216:219], v[20:23]
	v_mfma_f32_16x16x32_bf16 v[16:19], v[192:195], v[216:219], v[16:19]
	v_mfma_f32_16x16x32_bf16 v[4:7], v[168:171], v[224:227], v[4:7]
	v_mfma_f32_16x16x32_bf16 v[0:3], v[192:195], v[224:227], v[0:3]
	s_barrier
	s_setprio 0
	v_add_u32_e32 v155, s93, v149
	s_add_i32 s68, 0, 0x1c000
	ds_read_b128 v[138:141], v155
	ds_read_b128 v[142:145], v155 offset:1024
	ds_read_b128 v[156:159], v155 offset:2048
	ds_read_b128 v[160:163], v155 offset:3072
	v_add_u32_e32 v155, s68, v149
	ds_read_b128 v[164:167], v155
	ds_read_b128 v[168:171], v155 offset:1024
	ds_read_b128 v[172:175], v155 offset:2048
	ds_read_b128 v[192:195], v155 offset:3072
	s_add_u32 s46, s46, s48
	s_addc_u32 s47, s47, 0
	s_mov_b32 m0, s34
	v_lshl_add_u64 v[230:231], s[46:47], 0, v[132:133]
	ds_read_b128 v[196:199], v151 offset:32768
	ds_read_b128 v[200:203], v151 offset:33792
	ds_read_b128 v[204:207], v151 offset:34816
	ds_read_b128 v[208:211], v151 offset:35840
	ds_read_b128 v[212:215], v151 offset:36864
	ds_read_b128 v[216:219], v151 offset:37888
	ds_read_b128 v[220:223], v151 offset:38912
	ds_read_b128 v[224:227], v151 offset:39936
	global_load_lds_dwordx4 v[230:231], off
	v_lshl_add_u64 v[230:231], s[46:47], 0, v[130:131]
	s_mov_b32 m0, s95
	s_nop 0
	global_load_lds_dwordx4 v[230:231], off
	s_waitcnt vmcnt(8)
	s_waitcnt lgkmcnt(0)
	s_setprio 1
	s_barrier
	v_mfma_f32_16x16x32_bf16 v[124:127], v[138:141], v[196:199], v[124:127]
	v_mfma_f32_16x16x32_bf16 v[120:123], v[156:159], v[196:199], v[120:123]
	v_mfma_f32_16x16x32_bf16 v[108:111], v[138:141], v[204:207], v[108:111]
	v_mfma_f32_16x16x32_bf16 v[104:107], v[156:159], v[204:207], v[104:107]
	v_mfma_f32_16x16x32_bf16 v[92:95], v[138:141], v[212:215], v[92:95]
	v_mfma_f32_16x16x32_bf16 v[88:91], v[156:159], v[212:215], v[88:91]
	v_mfma_f32_16x16x32_bf16 v[76:79], v[138:141], v[220:223], v[76:79]
	v_mfma_f32_16x16x32_bf16 v[72:75], v[156:159], v[220:223], v[72:75]
	v_mfma_f32_16x16x32_bf16 v[124:127], v[142:145], v[200:203], v[124:127]
	v_mfma_f32_16x16x32_bf16 v[120:123], v[160:163], v[200:203], v[120:123]
	v_mfma_f32_16x16x32_bf16 v[108:111], v[142:145], v[208:211], v[108:111]
	v_mfma_f32_16x16x32_bf16 v[104:107], v[160:163], v[208:211], v[104:107]
	v_mfma_f32_16x16x32_bf16 v[92:95], v[142:145], v[216:219], v[92:95]
	v_mfma_f32_16x16x32_bf16 v[88:91], v[160:163], v[216:219], v[88:91]
	v_mfma_f32_16x16x32_bf16 v[76:79], v[142:145], v[224:227], v[76:79]
	v_mfma_f32_16x16x32_bf16 v[72:75], v[160:163], v[224:227], v[72:75]
	v_mfma_f32_16x16x32_bf16 v[116:119], v[164:167], v[196:199], v[116:119]
	v_mfma_f32_16x16x32_bf16 v[112:115], v[172:175], v[196:199], v[112:115]
	v_mfma_f32_16x16x32_bf16 v[100:103], v[164:167], v[204:207], v[100:103]
	v_mfma_f32_16x16x32_bf16 v[96:99], v[172:175], v[204:207], v[96:99]
	v_mfma_f32_16x16x32_bf16 v[84:87], v[164:167], v[212:215], v[84:87]
	v_mfma_f32_16x16x32_bf16 v[80:83], v[172:175], v[212:215], v[80:83]
	v_mfma_f32_16x16x32_bf16 v[68:71], v[164:167], v[220:223], v[68:71]
	v_mfma_f32_16x16x32_bf16 v[64:67], v[172:175], v[220:223], v[64:67]
	v_mfma_f32_16x16x32_bf16 v[116:119], v[168:171], v[200:203], v[116:119]
	v_mfma_f32_16x16x32_bf16 v[112:115], v[192:195], v[200:203], v[112:115]
	v_mfma_f32_16x16x32_bf16 v[100:103], v[168:171], v[208:211], v[100:103]
	v_mfma_f32_16x16x32_bf16 v[96:99], v[192:195], v[208:211], v[96:99]
	v_mfma_f32_16x16x32_bf16 v[84:87], v[168:171], v[216:219], v[84:87]
	v_mfma_f32_16x16x32_bf16 v[80:83], v[192:195], v[216:219], v[80:83]
	v_mfma_f32_16x16x32_bf16 v[68:71], v[168:171], v[224:227], v[68:71]
	v_mfma_f32_16x16x32_bf16 v[64:67], v[192:195], v[224:227], v[64:67]
	s_barrier
; #define PG8_STAGE(bufoff, gbase, voff) do { _Pragma("unroll") for (int _i = 0; _i < 2; ++_i) \
;         __builtin_amdgcn_global_load_lds((const unsigned*)((const char*)(gbase) + (voff)[_i]), (PG8_LAS unsigned*)(lds + (bufoff) + ldsw + _i * 8192), 16, 0, 0); } while (0)
; #define PG8_LDA(dst, b, h) do { _Pragma("unroll") for (int m = 0; m < 4; ++m) _Pragma("unroll") for (int k = 0; k < 2; ++k) dst[m][k] = *(const PG8_LAS bf16x8*)(lds + PG8_SA(b, h) + aoff + m * 2048 + k * 1024); } while (0)
; #define PG8_MMA(ai, bj, At, Bt) do { __builtin_amdgcn_s_setprio(1); _Pragma("unroll") for (int m = 0; m < 4; ++m) _Pragma("unroll") for (int n = 0; n < 2; ++n) _Pragma("unroll") for (int k = 0; k < 2; ++k) \
;         acc[ai][bj][m][n] = __builtin_amdgcn_mfma_f32_16x16x32_bf16(Bt[n][k], At[m][k], acc[ai][bj][m][n], 0, 0, 0); __builtin_amdgcn_s_setprio(0); } while (0)
; #define PG8_WAIT_V(n) asm volatile("s_waitcnt vmcnt(" #n ")" ::: "memory")
; #define PG8_WAIT_L(n) asm volatile("s_waitcnt lgkmcnt(" #n ")" ::: "memory")
; #define PG8_BAR __builtin_amdgcn_s_barrier()
; #define PG8_SCHED __builtin_amdgcn_sched_barrier(0)
; template <class Epi, class Sched, bool ALIGN_EPI = false, bool SP2 = false>
; __device__ __forceinline__ void gemm_phase(PG8_LAS unsigned char* lds, const Gemm g, const Sched& S, const Epi& E) {
;     ...
;             PG8_LDA(At, 1, 1); PG8_STAGE(PG8_SB(1, 0), b3, voffB); PG8_STAGE(PG8_SB(1, 1), b3 + hstep, voffB); PG8_STAGE(PG8_SA(1, 0), a3, voffA);
;             PG8_WAIT_V(8); PG8_WAIT_L(0); PG8_BAR; PG8_MMA(1, 0, At, B0); PG8_MMA(1, 1, At, B1); PG8_BAR; PG8_SCHED;
	s_setprio 0
	s_add_i32 s46, s93, s63
	v_lshl_add_u64 v[146:147], v[146:147], 0, s[18:19]
	s_mov_b32 m0, s46
	ds_read_b128 v[196:199], v151 offset:49152
	ds_read_b128 v[200:203], v151 offset:50176
	ds_read_b128 v[204:207], v151 offset:51200
	ds_read_b128 v[208:211], v151 offset:52224
	ds_read_b128 v[212:215], v151 offset:53248
	ds_read_b128 v[216:219], v151 offset:54272
	ds_read_b128 v[220:223], v151 offset:55296
	ds_read_b128 v[224:227], v151 offset:56320
	global_load_lds_dwordx4 v[146:147], off
	v_lshl_add_u64 v[146:147], v[182:183], 0, s[18:19]
	s_add_i32 m0, s46, 0x2000
	s_add_i32 s46, s68, s63
	global_load_lds_dwordx4 v[146:147], off
	v_lshl_add_u64 v[146:147], v[184:185], 0, s[18:19]
	s_mov_b32 m0, s46
	s_nop 0
	global_load_lds_dwordx4 v[146:147], off
	v_lshl_add_u64 v[146:147], v[188:189], 0, s[18:19]
	s_add_i32 m0, s46, 0x2000
	s_nop 0
	global_load_lds_dwordx4 v[146:147], off
	v_lshl_add_u64 v[146:147], v[190:191], 0, s[18:19]
	s_mov_b32 m0, s0
	s_nop 0
	global_load_lds_dwordx4 v[146:147], off
	v_lshl_add_u64 v[146:147], v[228:229], 0, s[18:19]
	s_mov_b32 m0, s58
	s_nop 0
	global_load_lds_dwordx4 v[146:147], off
	s_waitcnt vmcnt(8)
	s_waitcnt lgkmcnt(0)
	s_setprio 1
	s_barrier
	v_mfma_f32_16x16x32_bf16 v[60:63], v[138:141], v[196:199], v[60:63]
	v_mfma_f32_16x16x32_bf16 v[56:59], v[156:159], v[196:199], v[56:59]
	v_mfma_f32_16x16x32_bf16 v[44:47], v[138:141], v[204:207], v[44:47]
	v_mfma_f32_16x16x32_bf16 v[40:43], v[156:159], v[204:207], v[40:43]
	v_mfma_f32_16x16x32_bf16 v[28:31], v[138:141], v[212:215], v[28:31]
	v_mfma_f32_16x16x32_bf16 v[24:27], v[156:159], v[212:215], v[24:27]
	v_mfma_f32_16x16x32_bf16 v[12:15], v[138:141], v[220:223], v[12:15]
	v_mfma_f32_16x16x32_bf16 v[8:11], v[156:159], v[220:223], v[8:11]
	v_mfma_f32_16x16x32_bf16 v[60:63], v[142:145], v[200:203], v[60:63]
	v_mfma_f32_16x16x32_bf16 v[56:59], v[160:163], v[200:203], v[56:59]
	v_mfma_f32_16x16x32_bf16 v[44:47], v[142:145], v[208:211], v[44:47]
	v_mfma_f32_16x16x32_bf16 v[40:43], v[160:163], v[208:211], v[40:43]
	v_mfma_f32_16x16x32_bf16 v[28:31], v[142:145], v[216:219], v[28:31]
	v_mfma_f32_16x16x32_bf16 v[24:27], v[160:163], v[216:219], v[24:27]
	v_mfma_f32_16x16x32_bf16 v[12:15], v[142:145], v[224:227], v[12:15]
	v_mfma_f32_16x16x32_bf16 v[8:11], v[160:163], v[224:227], v[8:11]
	v_mfma_f32_16x16x32_bf16 v[52:55], v[164:167], v[196:199], v[52:55]
	v_mfma_f32_16x16x32_bf16 v[48:51], v[172:175], v[196:199], v[48:51]
	v_mfma_f32_16x16x32_bf16 v[36:39], v[164:167], v[204:207], v[36:39]
	v_mfma_f32_16x16x32_bf16 v[32:35], v[172:175], v[204:207], v[32:35]
	v_mfma_f32_16x16x32_bf16 v[20:23], v[164:167], v[212:215], v[20:23]
	v_mfma_f32_16x16x32_bf16 v[16:19], v[172:175], v[212:215], v[16:19]
	v_mfma_f32_16x16x32_bf16 v[4:7], v[164:167], v[220:223], v[4:7]
	v_mfma_f32_16x16x32_bf16 v[0:3], v[172:175], v[220:223], v[0:3]
	v_mfma_f32_16x16x32_bf16 v[52:55], v[168:171], v[200:203], v[52:55]
	v_mfma_f32_16x16x32_bf16 v[48:51], v[192:195], v[200:203], v[48:51]
	v_mfma_f32_16x16x32_bf16 v[36:39], v[168:171], v[208:211], v[36:39]
	v_mfma_f32_16x16x32_bf16 v[32:35], v[192:195], v[208:211], v[32:35]
	v_mfma_f32_16x16x32_bf16 v[20:23], v[168:171], v[216:219], v[20:23]
	v_mfma_f32_16x16x32_bf16 v[16:19], v[192:195], v[216:219], v[16:19]
	v_mfma_f32_16x16x32_bf16 v[4:7], v[168:171], v[224:227], v[4:7]
	v_mfma_f32_16x16x32_bf16 v[0:3], v[192:195], v[224:227], v[0:3]
	s_barrier
	s_setprio 0
	s_add_u32 s44, s44, 0x100
	s_addc_u32 s45, s45, 0
	s_add_u32 s86, s86, 0x100
	s_addc_u32 s87, s87, 0
	s_cmp_ge_u32 vcc_lo, s14
	s_mov_b32 s46, vcc_lo
	s_cbranch_scc1 .Lpeel_exit_218

; #define PG8_BAR __builtin_amdgcn_s_barrier()
; template <class Epi, class Sched, bool ALIGN_EPI = false, bool SP2 = false>
; __device__ __forceinline__ void gemm_phase(PG8_LAS unsigned char* lds, const Gemm g, const Sched& S, const Epi& E) {
;     ...
;         if constexpr (ALIGN_EPI) { if (wr == 0) PG8_BAR; }
.Lpeel_exit_218:
	s_and_b64 vcc, exec, s[36:37]
	s_cbranch_vccz .LBB0_221
	s_barrier

; #define PG8_STAGE(bufoff, gbase, voff) do { _Pragma("unroll") for (int _i = 0; _i < 2; ++_i) \
;         __builtin_amdgcn_global_load_lds((const unsigned*)((const char*)(gbase) + (voff)[_i]), (PG8_LAS unsigned*)(lds + (bufoff) + ldsw + _i * 8192), 16, 0, 0); } while (0)
; #define PG8_LDA(dst, b, h) do { _Pragma("unroll") for (int m = 0; m < 4; ++m) _Pragma("unroll") for (int k = 0; k < 2; ++k) dst[m][k] = *(const PG8_LAS bf16x8*)(lds + PG8_SA(b, h) + aoff + m * 2048 + k * 1024); } while (0)
; #define PG8_LDB(dst, b, h) do { _Pragma("unroll") for (int n = 0; n < 2; ++n) _Pragma("unroll") for (int k = 0; k < 2; ++k) dst[n][k] = *(const PG8_LAS bf16x8*)(lds + PG8_SB(b, h) + boff + n * 2048 + k * 1024); } while (0)
; #define PG8_MMA(ai, bj, At, Bt) do { __builtin_amdgcn_s_setprio(1); _Pragma("unroll") for (int m = 0; m < 4; ++m) _Pragma("unroll") for (int n = 0; n < 2; ++n) _Pragma("unroll") for (int k = 0; k < 2; ++k) \
;         acc[ai][bj][m][n] = __builtin_amdgcn_mfma_f32_16x16x32_bf16(Bt[n][k], At[m][k], acc[ai][bj][m][n], 0, 0, 0); __builtin_amdgcn_s_setprio(0); } while (0)
; #define PG8_WAIT_V(n) asm volatile("s_waitcnt vmcnt(" #n ")" ::: "memory")
; #define PG8_WAIT_L(n) asm volatile("s_waitcnt lgkmcnt(" #n ")" ::: "memory")
; template <class Epi, class Sched, bool ALIGN_EPI = false, bool SP2 = false>
; __device__ __forceinline__ void gemm_phase(PG8_LAS unsigned char* lds, const Gemm g, const Sched& S, const Epi& E) {
;     ...
;             const bool last = (t == nt - 2);
;             const char* a1 = cA + (size_t)(t + 1) * kstep;
;             const char* a2 = last ? nA : cA + (size_t)(t + 2) * kstep; const char* b2 = last ? nB : cB + (size_t)(t + 2) * kstep;
;             const char* a3 = a2 + kstep; const char* b3 = b2 + kstep;
;             if (last && has_next) S.a_ready(nxt);
;             if constexpr (SP2) {
;             PG8_LDB(B0, 0, 0); PG8_LDB(B1, 0, 1); PG8_SCHED; PG8_LDA(At, 0, 0); PG8_STAGE(PG8_SA(1, 1), a1 + hstep, voffA);
;             PG8_WAIT_V(8); PG8_WAIT_L(0); PG8_BAR; PG8_MMA(0, 0, At, B0); PG8_MMA(0, 1, At, B1); PG8_BAR; PG8_SCHED;
;             PG8_LDA(At, 0, 1); PG8_STAGE(PG8_SB(0, 0), b2, voffB); PG8_STAGE(PG8_SB(0, 1), b2 + hstep, voffB); PG8_STAGE(PG8_SA(0, 0), a2, voffA);
;             PG8_WAIT_V(8); PG8_WAIT_L(0); PG8_BAR; PG8_MMA(1, 0, At, B0); PG8_MMA(1, 1, At, B1); PG8_BAR; PG8_SCHED;
.LBB0_330:
	s_ashr_i32 s45, s44, 31
	s_lshl_b64 s[46:47], s[44:45], 20
	s_add_u32 s46, s12, s46
	s_addc_u32 s47, s13, s47
	s_and_b64 s[48:49], s[40:41], exec
	s_cselect_b32 s45, s47, s75
	s_cselect_b32 s59, s46, s74
	s_ashr_i32 s43, s42, 31
	s_lshl_b64 s[48:49], s[42:43], 20
	s_add_u32 s48, s14, s48
	s_addc_u32 s49, s0, s49
	s_and_b64 s[78:79], s[40:41], exec
	s_cselect_b32 s43, s49, s77
	s_cselect_b32 s63, s48, s76
	s_add_u32 s74, s74, 0x80080
	s_addc_u32 s75, s75, 0
	s_add_u32 s71, s76, 0x100
	v_mov_b32_e32 v0, 0
	s_addc_u32 s80, s77, 0
	s_mov_b32 s81, -2
	s_waitcnt vmcnt(0)
	s_add_u32 s68, s74, 0xfff80080
	s_addc_u32 s69, s75, -1
	s_add_i32 s82, 0, 0x10000
	s_cmp_eq_u32 s81, 28
	s_cselect_b32 s79, s45, s69
	s_cselect_b32 s78, s59, s68
	v_add_u32_e32 v140, s82, v143
	s_cselect_b32 s77, s43, s80
	s_cselect_b32 s76, s63, s71
	s_add_i32 s68, 0, 0x14000
	ds_read_b128 v[146:149], v140
	ds_read_b128 v[156:159], v140 offset:1024
	ds_read_b128 v[160:163], v140 offset:2048
	ds_read_b128 v[164:167], v140 offset:3072
	v_add_u32_e32 v140, s68, v143
	ds_read_b128 v[168:171], v140
	ds_read_b128 v[172:175], v140 offset:1024
	ds_read_b128 v[192:195], v140 offset:2048
	ds_read_b128 v[196:199], v140 offset:3072
	v_lshl_add_u64 v[140:141], s[74:75], 0, v[136:137]
	s_add_i32 m0, s16, 0xc000
	ds_read_b128 v[200:203], v145
	ds_read_b128 v[204:207], v145 offset:1024
	ds_read_b128 v[208:211], v145 offset:2048
	ds_read_b128 v[212:215], v145 offset:3072
	ds_read_b128 v[216:219], v145 offset:4096
	ds_read_b128 v[220:223], v145 offset:5120
	ds_read_b128 v[224:227], v145 offset:6144
	ds_read_b128 v[228:231], v145 offset:7168
	global_load_lds_dwordx4 v[140:141], off
	v_lshl_add_u64 v[140:141], s[74:75], 0, v[138:139]
	s_add_i32 m0, s16, 0xe000
	s_nop 0
	global_load_lds_dwordx4 v[140:141], off
	s_waitcnt vmcnt(8)
	s_waitcnt lgkmcnt(0)
	s_setprio 1
	s_barrier
	v_mfma_f32_16x16x32_bf16 v[116:119], v[146:149], v[200:203], 0
	v_mfma_f32_16x16x32_bf16 v[112:115], v[160:163], v[200:203], 0
	v_mfma_f32_16x16x32_bf16 v[104:107], v[146:149], v[208:211], 0
	v_mfma_f32_16x16x32_bf16 v[96:99], v[160:163], v[208:211], 0
	v_mfma_f32_16x16x32_bf16 v[88:91], v[146:149], v[216:219], 0
	v_mfma_f32_16x16x32_bf16 v[80:83], v[160:163], v[216:219], 0
	v_mfma_f32_16x16x32_bf16 v[72:75], v[146:149], v[224:227], 0
	v_mfma_f32_16x16x32_bf16 v[64:67], v[160:163], v[224:227], 0
	v_mfma_f32_16x16x32_bf16 v[116:119], v[156:159], v[204:207], v[116:119]
	v_mfma_f32_16x16x32_bf16 v[112:115], v[164:167], v[204:207], v[112:115]
	v_mfma_f32_16x16x32_bf16 v[104:107], v[156:159], v[212:215], v[104:107]
	v_mfma_f32_16x16x32_bf16 v[96:99], v[164:167], v[212:215], v[96:99]
	v_mfma_f32_16x16x32_bf16 v[88:91], v[156:159], v[220:223], v[88:91]
	v_mfma_f32_16x16x32_bf16 v[80:83], v[164:167], v[220:223], v[80:83]
	v_mfma_f32_16x16x32_bf16 v[72:75], v[156:159], v[228:231], v[72:75]
	v_mfma_f32_16x16x32_bf16 v[64:67], v[164:167], v[228:231], v[64:67]
	v_mfma_f32_16x16x32_bf16 v[124:127], v[168:171], v[200:203], 0
	v_mfma_f32_16x16x32_bf16 v[120:123], v[192:195], v[200:203], 0
	v_mfma_f32_16x16x32_bf16 v[108:111], v[168:171], v[208:211], 0
	v_mfma_f32_16x16x32_bf16 v[100:103], v[192:195], v[208:211], 0
	v_mfma_f32_16x16x32_bf16 v[92:95], v[168:171], v[216:219], 0
	v_mfma_f32_16x16x32_bf16 v[84:87], v[192:195], v[216:219], 0
	v_mfma_f32_16x16x32_bf16 v[76:79], v[168:171], v[224:227], 0
	v_mfma_f32_16x16x32_bf16 v[68:71], v[192:195], v[224:227], 0
	v_mfma_f32_16x16x32_bf16 v[124:127], v[172:175], v[204:207], v[124:127]
	v_mfma_f32_16x16x32_bf16 v[120:123], v[196:199], v[204:207], v[120:123]
	v_mfma_f32_16x16x32_bf16 v[108:111], v[172:175], v[212:215], v[108:111]
	v_mfma_f32_16x16x32_bf16 v[100:103], v[196:199], v[212:215], v[100:103]
	v_mfma_f32_16x16x32_bf16 v[92:95], v[172:175], v[220:223], v[92:95]
	v_mfma_f32_16x16x32_bf16 v[84:87], v[196:199], v[220:223], v[84:87]
	v_mfma_f32_16x16x32_bf16 v[76:79], v[172:175], v[228:231], v[76:79]
	v_mfma_f32_16x16x32_bf16 v[68:71], v[196:199], v[228:231], v[68:71]
	s_barrier
	s_setprio 0
	s_add_i32 s69, s82, s15
	v_lshl_add_u64 v[140:141], s[76:77], 0, v[152:153]
	s_mov_b32 m0, s69
	ds_read_b128 v[200:203], v145 offset:16384
	ds_read_b128 v[204:207], v145 offset:17408
	ds_read_b128 v[208:211], v145 offset:18432
	ds_read_b128 v[212:215], v145 offset:19456
	ds_read_b128 v[216:219], v145 offset:20480
	ds_read_b128 v[220:223], v145 offset:21504
	ds_read_b128 v[224:227], v145 offset:22528
	ds_read_b128 v[228:231], v145 offset:23552
	global_load_lds_dwordx4 v[140:141], off
	s_add_i32 m0, s69, 0x2000
	s_add_u32 s82, s76, 0x80000
	v_lshl_add_u64 v[150:151], s[76:77], 0, v[128:129]
	s_addc_u32 s83, s77, 0
	s_add_i32 s68, s68, s15
	global_load_lds_dwordx4 v[150:151], off
	v_lshl_add_u64 v[182:183], s[82:83], 0, v[152:153]
	s_mov_b32 m0, s68
	v_lshl_add_u64 v[184:185], s[78:79], 0, v[130:131]
	global_load_lds_dwordx4 v[182:183], off
	v_lshl_add_u64 v[182:183], s[82:83], 0, v[128:129]
	s_add_i32 m0, s68, 0x2000
	s_nop 0
	global_load_lds_dwordx4 v[182:183], off
	v_lshl_add_u64 v[182:183], s[78:79], 0, v[132:133]
	s_mov_b32 m0, s16
	s_nop 0
	global_load_lds_dwordx4 v[182:183], off
	s_mov_b32 m0, s17
	s_nop 0
	global_load_lds_dwordx4 v[184:185], off
	s_waitcnt vmcnt(8)
	s_waitcnt lgkmcnt(0)
	s_setprio 1
	s_barrier
; #define PG8_STAGE(bufoff, gbase, voff) do { _Pragma("unroll") for (int _i = 0; _i < 2; ++_i) \
;         __builtin_amdgcn_global_load_lds((const unsigned*)((const char*)(gbase) + (voff)[_i]), (PG8_LAS unsigned*)(lds + (bufoff) + ldsw + _i * 8192), 16, 0, 0); } while (0)
; #define PG8_LDA(dst, b, h) do { _Pragma("unroll") for (int m = 0; m < 4; ++m) _Pragma("unroll") for (int k = 0; k < 2; ++k) dst[m][k] = *(const PG8_LAS bf16x8*)(lds + PG8_SA(b, h) + aoff + m * 2048 + k * 1024); } while (0)
; #define PG8_LDB(dst, b, h) do { _Pragma("unroll") for (int n = 0; n < 2; ++n) _Pragma("unroll") for (int k = 0; k < 2; ++k) dst[n][k] = *(const PG8_LAS bf16x8*)(lds + PG8_SB(b, h) + boff + n * 2048 + k * 1024); } while (0)
; #define PG8_MMA(ai, bj, At, Bt) do { __builtin_amdgcn_s_setprio(1); _Pragma("unroll") for (int m = 0; m < 4; ++m) _Pragma("unroll") for (int n = 0; n < 2; ++n) _Pragma("unroll") for (int k = 0; k < 2; ++k) \
;         acc[ai][bj][m][n] = __builtin_amdgcn_mfma_f32_16x16x32_bf16(Bt[n][k], At[m][k], acc[ai][bj][m][n], 0, 0, 0); __builtin_amdgcn_s_setprio(0); } while (0)
; #define PG8_WAIT_V(n) asm volatile("s_waitcnt vmcnt(" #n ")" ::: "memory")
; #define PG8_WAIT_L(n) asm volatile("s_waitcnt lgkmcnt(" #n ")" ::: "memory")
; #define PG8_BAR __builtin_amdgcn_s_barrier()
; #define PG8_SCHED __builtin_amdgcn_sched_barrier(0)
; template <class Epi, class Sched, bool ALIGN_EPI = false, bool SP2 = false>
; __device__ __forceinline__ void gemm_phase(PG8_LAS unsigned char* lds, const Gemm g, const Sched& S, const Epi& E) {
;     ...
;             PG8_WAIT_V(8); PG8_WAIT_L(0); PG8_BAR; PG8_MMA(1, 0, At, B0); PG8_MMA(1, 1, At, B1); PG8_BAR; PG8_SCHED;
;             PG8_LDB(B0, 1, 0); PG8_LDB(B1, 1, 1); PG8_SCHED; PG8_LDA(At, 1, 0); PG8_STAGE(PG8_SA(0, 1), a2 + hstep, voffA);
;             PG8_WAIT_V(8); PG8_WAIT_L(0); PG8_BAR; PG8_MMA(0, 0, At, B0); PG8_MMA(0, 1, At, B1); PG8_BAR; PG8_SCHED;
;             PG8_LDA(At, 1, 1); PG8_STAGE(PG8_SB(1, 0), b3, voffB); PG8_STAGE(PG8_SB(1, 1), b3 + hstep, voffB); PG8_STAGE(PG8_SA(1, 0), a3, voffA);
	v_mfma_f32_16x16x32_bf16 v[56:59], v[146:149], v[200:203], 0
	v_mfma_f32_16x16x32_bf16 v[48:51], v[160:163], v[200:203], 0
	v_mfma_f32_16x16x32_bf16 v[40:43], v[146:149], v[208:211], 0
	v_mfma_f32_16x16x32_bf16 v[32:35], v[160:163], v[208:211], 0
	v_mfma_f32_16x16x32_bf16 v[24:27], v[146:149], v[216:219], 0
	v_mfma_f32_16x16x32_bf16 v[16:19], v[160:163], v[216:219], 0
	v_mfma_f32_16x16x32_bf16 v[8:11], v[146:149], v[224:227], 0
	v_mfma_f32_16x16x32_bf16 v[4:7], v[160:163], v[224:227], 0
	v_mfma_f32_16x16x32_bf16 v[56:59], v[156:159], v[204:207], v[56:59]
	v_mfma_f32_16x16x32_bf16 v[48:51], v[164:167], v[204:207], v[48:51]
	v_mfma_f32_16x16x32_bf16 v[40:43], v[156:159], v[212:215], v[40:43]
	v_mfma_f32_16x16x32_bf16 v[32:35], v[164:167], v[212:215], v[32:35]
	v_mfma_f32_16x16x32_bf16 v[24:27], v[156:159], v[220:223], v[24:27]
	v_mfma_f32_16x16x32_bf16 v[16:19], v[164:167], v[220:223], v[16:19]
	v_mfma_f32_16x16x32_bf16 v[8:11], v[156:159], v[228:231], v[8:11]
	v_mfma_f32_16x16x32_bf16 v[4:7], v[164:167], v[228:231], v[4:7]
	v_mfma_f32_16x16x32_bf16 v[60:63], v[168:171], v[200:203], 0
	v_mfma_f32_16x16x32_bf16 v[52:55], v[192:195], v[200:203], 0
	v_mfma_f32_16x16x32_bf16 v[44:47], v[168:171], v[208:211], 0
	v_mfma_f32_16x16x32_bf16 v[36:39], v[192:195], v[208:211], 0
	v_mfma_f32_16x16x32_bf16 v[28:31], v[168:171], v[216:219], 0
	v_mfma_f32_16x16x32_bf16 v[20:23], v[192:195], v[216:219], 0
	v_mfma_f32_16x16x32_bf16 v[12:15], v[168:171], v[224:227], 0
	v_mfma_f32_16x16x32_bf16 v[0:3], v[192:195], v[224:227], 0
	v_mfma_f32_16x16x32_bf16 v[60:63], v[172:175], v[204:207], v[60:63]
	v_mfma_f32_16x16x32_bf16 v[52:55], v[196:199], v[204:207], v[52:55]
	v_mfma_f32_16x16x32_bf16 v[44:47], v[172:175], v[212:215], v[44:47]
	v_mfma_f32_16x16x32_bf16 v[36:39], v[196:199], v[212:215], v[36:39]
	v_mfma_f32_16x16x32_bf16 v[28:31], v[172:175], v[220:223], v[28:31]
	v_mfma_f32_16x16x32_bf16 v[20:23], v[196:199], v[220:223], v[20:23]
	v_mfma_f32_16x16x32_bf16 v[12:15], v[172:175], v[228:231], v[12:15]
	v_mfma_f32_16x16x32_bf16 v[0:3], v[196:199], v[228:231], v[0:3]
	s_barrier
	s_setprio 0
	v_add_u32_e32 v155, s93, v143
	s_add_i32 s68, 0, 0x1c000
	ds_read_b128 v[146:149], v155
	ds_read_b128 v[156:159], v155 offset:1024
	ds_read_b128 v[160:163], v155 offset:2048
	ds_read_b128 v[164:167], v155 offset:3072
	v_add_u32_e32 v155, s68, v143
	ds_read_b128 v[168:171], v155
	ds_read_b128 v[172:175], v155 offset:1024
	ds_read_b128 v[192:195], v155 offset:2048
	ds_read_b128 v[196:199], v155 offset:3072
	s_add_u32 s78, s78, 0x80000
	s_addc_u32 s79, s79, 0
	s_mov_b32 m0, s22
	v_lshl_add_u64 v[188:189], s[78:79], 0, v[132:133]
	ds_read_b128 v[200:203], v145 offset:32768
	ds_read_b128 v[204:207], v145 offset:33792
	ds_read_b128 v[208:211], v145 offset:34816
	ds_read_b128 v[212:215], v145 offset:35840
	ds_read_b128 v[216:219], v145 offset:36864
	ds_read_b128 v[220:223], v145 offset:37888
	ds_read_b128 v[224:227], v145 offset:38912
	ds_read_b128 v[228:231], v145 offset:39936
	global_load_lds_dwordx4 v[188:189], off
	v_lshl_add_u64 v[188:189], s[78:79], 0, v[130:131]
	s_mov_b32 m0, s23
	s_nop 0
	global_load_lds_dwordx4 v[188:189], off
	s_waitcnt vmcnt(8)
	s_waitcnt lgkmcnt(0)
	s_setprio 1
	s_barrier
	v_mfma_f32_16x16x32_bf16 v[116:119], v[146:149], v[200:203], v[116:119]
	v_mfma_f32_16x16x32_bf16 v[112:115], v[160:163], v[200:203], v[112:115]
	v_mfma_f32_16x16x32_bf16 v[104:107], v[146:149], v[208:211], v[104:107]
	v_mfma_f32_16x16x32_bf16 v[96:99], v[160:163], v[208:211], v[96:99]
	v_mfma_f32_16x16x32_bf16 v[88:91], v[146:149], v[216:219], v[88:91]
	v_mfma_f32_16x16x32_bf16 v[80:83], v[160:163], v[216:219], v[80:83]
	v_mfma_f32_16x16x32_bf16 v[72:75], v[146:149], v[224:227], v[72:75]
	v_mfma_f32_16x16x32_bf16 v[64:67], v[160:163], v[224:227], v[64:67]
	v_mfma_f32_16x16x32_bf16 v[116:119], v[156:159], v[204:207], v[116:119]
	v_mfma_f32_16x16x32_bf16 v[112:115], v[164:167], v[204:207], v[112:115]
	v_mfma_f32_16x16x32_bf16 v[104:107], v[156:159], v[212:215], v[104:107]
	v_mfma_f32_16x16x32_bf16 v[96:99], v[164:167], v[212:215], v[96:99]
	v_mfma_f32_16x16x32_bf16 v[88:91], v[156:159], v[220:223], v[88:91]
	v_mfma_f32_16x16x32_bf16 v[80:83], v[164:167], v[220:223], v[80:83]
	v_mfma_f32_16x16x32_bf16 v[72:75], v[156:159], v[228:231], v[72:75]
	v_mfma_f32_16x16x32_bf16 v[64:67], v[164:167], v[228:231], v[64:67]
	v_mfma_f32_16x16x32_bf16 v[124:127], v[168:171], v[200:203], v[124:127]
	v_mfma_f32_16x16x32_bf16 v[120:123], v[192:195], v[200:203], v[120:123]
	v_mfma_f32_16x16x32_bf16 v[108:111], v[168:171], v[208:211], v[108:111]
	v_mfma_f32_16x16x32_bf16 v[100:103], v[192:195], v[208:211], v[100:103]
	v_mfma_f32_16x16x32_bf16 v[92:95], v[168:171], v[216:219], v[92:95]
	v_mfma_f32_16x16x32_bf16 v[84:87], v[192:195], v[216:219], v[84:87]
	v_mfma_f32_16x16x32_bf16 v[76:79], v[168:171], v[224:227], v[76:79]
	v_mfma_f32_16x16x32_bf16 v[68:71], v[192:195], v[224:227], v[68:71]
	v_mfma_f32_16x16x32_bf16 v[124:127], v[172:175], v[204:207], v[124:127]
	v_mfma_f32_16x16x32_bf16 v[120:123], v[196:199], v[204:207], v[120:123]
	v_mfma_f32_16x16x32_bf16 v[108:111], v[172:175], v[212:215], v[108:111]
	v_mfma_f32_16x16x32_bf16 v[100:103], v[196:199], v[212:215], v[100:103]
	v_mfma_f32_16x16x32_bf16 v[92:95], v[172:175], v[220:223], v[92:95]
	v_mfma_f32_16x16x32_bf16 v[84:87], v[196:199], v[220:223], v[84:87]
	v_mfma_f32_16x16x32_bf16 v[76:79], v[172:175], v[228:231], v[76:79]
	v_mfma_f32_16x16x32_bf16 v[68:71], v[196:199], v[228:231], v[68:71]
	s_barrier
; #define PG8_STAGE(bufoff, gbase, voff) do { _Pragma("unroll") for (int _i = 0; _i < 2; ++_i) \
;         __builtin_amdgcn_global_load_lds((const unsigned*)((const char*)(gbase) + (voff)[_i]), (PG8_LAS unsigned*)(lds + (bufoff) + ldsw + _i * 8192), 16, 0, 0); } while (0)
; #define PG8_LDA(dst, b, h) do { _Pragma("unroll") for (int m = 0; m < 4; ++m) _Pragma("unroll") for (int k = 0; k < 2; ++k) dst[m][k] = *(const PG8_LAS bf16x8*)(lds + PG8_SA(b, h) + aoff + m * 2048 + k * 1024); } while (0)
; #define PG8_MMA(ai, bj, At, Bt) do { __builtin_amdgcn_s_setprio(1); _Pragma("unroll") for (int m = 0; m < 4; ++m) _Pragma("unroll") for (int n = 0; n < 2; ++n) _Pragma("unroll") for (int k = 0; k < 2; ++k) \
;         acc[ai][bj][m][n] = __builtin_amdgcn_mfma_f32_16x16x32_bf16(Bt[n][k], At[m][k], acc[ai][bj][m][n], 0, 0, 0); __builtin_amdgcn_s_setprio(0); } while (0)
; #define PG8_WAIT_V(n) asm volatile("s_waitcnt vmcnt(" #n ")" ::: "memory")
; #define PG8_WAIT_L(n) asm volatile("s_waitcnt lgkmcnt(" #n ")" ::: "memory")
; #define PG8_BAR __builtin_amdgcn_s_barrier()
; #define PG8_SCHED __builtin_amdgcn_sched_barrier(0)
; template <class Epi, class Sched, bool ALIGN_EPI = false, bool SP2 = false>
; __device__ __forceinline__ void gemm_phase(PG8_LAS unsigned char* lds, const Gemm g, const Sched& S, const Epi& E) {
;     ...
;             PG8_LDA(At, 1, 1); PG8_STAGE(PG8_SB(1, 0), b3, voffB); PG8_STAGE(PG8_SB(1, 1), b3 + hstep, voffB); PG8_STAGE(PG8_SA(1, 0), a3, voffA);
;             PG8_WAIT_V(8); PG8_WAIT_L(0); PG8_BAR; PG8_MMA(1, 0, At, B0); PG8_MMA(1, 1, At, B1); PG8_BAR; PG8_SCHED;
	s_setprio 0
	s_add_i32 s69, s93, s15
	v_lshl_add_u64 v[140:141], v[140:141], 0, s[18:19]
	s_mov_b32 m0, s69
	ds_read_b128 v[200:203], v145 offset:49152
	ds_read_b128 v[204:207], v145 offset:50176
	ds_read_b128 v[208:211], v145 offset:51200
	ds_read_b128 v[212:215], v145 offset:52224
	ds_read_b128 v[216:219], v145 offset:53248
	ds_read_b128 v[220:223], v145 offset:54272
	ds_read_b128 v[224:227], v145 offset:55296
	ds_read_b128 v[228:231], v145 offset:56320
	global_load_lds_dwordx4 v[140:141], off
	s_add_i32 m0, s69, 0x2000
	s_add_u32 s76, s76, 0x80080
	v_lshl_add_u64 v[140:141], v[150:151], 0, s[18:19]
	s_addc_u32 s77, s77, 0
	s_add_i32 s68, s68, s15
	global_load_lds_dwordx4 v[140:141], off
	v_lshl_add_u64 v[140:141], s[76:77], 0, v[152:153]
	s_mov_b32 m0, s68
	s_nop 0
	global_load_lds_dwordx4 v[140:141], off
	v_lshl_add_u64 v[140:141], s[76:77], 0, v[128:129]
	s_add_i32 m0, s68, 0x2000
	s_nop 0
	global_load_lds_dwordx4 v[140:141], off
	v_lshl_add_u64 v[140:141], v[182:183], 0, s[18:19]
	s_mov_b32 m0, s26
	s_nop 0
	global_load_lds_dwordx4 v[140:141], off
	v_lshl_add_u64 v[140:141], v[184:185], 0, s[18:19]
	s_mov_b32 m0, s34
	s_nop 0
	global_load_lds_dwordx4 v[140:141], off
	s_waitcnt vmcnt(8)
	s_waitcnt lgkmcnt(0)
	s_setprio 1
	s_barrier
	v_mfma_f32_16x16x32_bf16 v[56:59], v[146:149], v[200:203], v[56:59]
	v_mfma_f32_16x16x32_bf16 v[48:51], v[160:163], v[200:203], v[48:51]
	v_mfma_f32_16x16x32_bf16 v[40:43], v[146:149], v[208:211], v[40:43]
	v_mfma_f32_16x16x32_bf16 v[32:35], v[160:163], v[208:211], v[32:35]
	v_mfma_f32_16x16x32_bf16 v[24:27], v[146:149], v[216:219], v[24:27]
	v_mfma_f32_16x16x32_bf16 v[16:19], v[160:163], v[216:219], v[16:19]
	v_mfma_f32_16x16x32_bf16 v[8:11], v[146:149], v[224:227], v[8:11]
	v_mfma_f32_16x16x32_bf16 v[4:7], v[160:163], v[224:227], v[4:7]
	v_mfma_f32_16x16x32_bf16 v[56:59], v[156:159], v[204:207], v[56:59]
	v_mfma_f32_16x16x32_bf16 v[48:51], v[164:167], v[204:207], v[48:51]
	v_mfma_f32_16x16x32_bf16 v[40:43], v[156:159], v[212:215], v[40:43]
	v_mfma_f32_16x16x32_bf16 v[32:35], v[164:167], v[212:215], v[32:35]
	v_mfma_f32_16x16x32_bf16 v[24:27], v[156:159], v[220:223], v[24:27]
	v_mfma_f32_16x16x32_bf16 v[16:19], v[164:167], v[220:223], v[16:19]
	v_mfma_f32_16x16x32_bf16 v[8:11], v[156:159], v[228:231], v[8:11]
	v_mfma_f32_16x16x32_bf16 v[4:7], v[164:167], v[228:231], v[4:7]
	v_mfma_f32_16x16x32_bf16 v[60:63], v[168:171], v[200:203], v[60:63]
	v_mfma_f32_16x16x32_bf16 v[52:55], v[192:195], v[200:203], v[52:55]
	v_mfma_f32_16x16x32_bf16 v[44:47], v[168:171], v[208:211], v[44:47]
	v_mfma_f32_16x16x32_bf16 v[36:39], v[192:195], v[208:211], v[36:39]
	v_mfma_f32_16x16x32_bf16 v[28:31], v[168:171], v[216:219], v[28:31]
	v_mfma_f32_16x16x32_bf16 v[20:23], v[192:195], v[216:219], v[20:23]
	v_mfma_f32_16x16x32_bf16 v[12:15], v[168:171], v[224:227], v[12:15]
	v_mfma_f32_16x16x32_bf16 v[0:3], v[192:195], v[224:227], v[0:3]
	v_mfma_f32_16x16x32_bf16 v[60:63], v[172:175], v[204:207], v[60:63]
	v_mfma_f32_16x16x32_bf16 v[52:55], v[196:199], v[204:207], v[52:55]
	v_mfma_f32_16x16x32_bf16 v[44:47], v[172:175], v[212:215], v[44:47]
	v_mfma_f32_16x16x32_bf16 v[36:39], v[196:199], v[212:215], v[36:39]
	v_mfma_f32_16x16x32_bf16 v[28:31], v[172:175], v[220:223], v[28:31]
	v_mfma_f32_16x16x32_bf16 v[20:23], v[196:199], v[220:223], v[20:23]
	v_mfma_f32_16x16x32_bf16 v[12:15], v[172:175], v[228:231], v[12:15]
	v_mfma_f32_16x16x32_bf16 v[0:3], v[196:199], v[228:231], v[0:3]
	s_barrier
	s_setprio 0
	s_add_i32 s81, s81, 2
	s_add_u32 s74, s74, 0x100
	s_addc_u32 s75, s75, 0
	s_add_u32 s71, s71, 0x100
	s_addc_u32 s80, s80, 0
	s_cmp_gt_u32 s81, 29
	s_cbranch_scc1 .Lpeel_exit_331

; #define PG8_STAGE(bufoff, gbase, voff) do { _Pragma("unroll") for (int _i = 0; _i < 2; ++_i) \
;         __builtin_amdgcn_global_load_lds((const unsigned*)((const char*)(gbase) + (voff)[_i]), (PG8_LAS unsigned*)(lds + (bufoff) + ldsw + _i * 8192), 16, 0, 0); } while (0)
; #define PG8_LDA(dst, b, h) do { _Pragma("unroll") for (int m = 0; m < 4; ++m) _Pragma("unroll") for (int k = 0; k < 2; ++k) dst[m][k] = *(const PG8_LAS bf16x8*)(lds + PG8_SA(b, h) + aoff + m * 2048 + k * 1024); } while (0)
; #define PG8_LDB(dst, b, h) do { _Pragma("unroll") for (int n = 0; n < 2; ++n) _Pragma("unroll") for (int k = 0; k < 2; ++k) dst[n][k] = *(const PG8_LAS bf16x8*)(lds + PG8_SB(b, h) + boff + n * 2048 + k * 1024); } while (0)
; #define PG8_MMA(ai, bj, At, Bt) do { __builtin_amdgcn_s_setprio(1); _Pragma("unroll") for (int m = 0; m < 4; ++m) _Pragma("unroll") for (int n = 0; n < 2; ++n) _Pragma("unroll") for (int k = 0; k < 2; ++k) \
;         acc[ai][bj][m][n] = __builtin_amdgcn_mfma_f32_16x16x32_bf16(Bt[n][k], At[m][k], acc[ai][bj][m][n], 0, 0, 0); __builtin_amdgcn_s_setprio(0); } while (0)
; #define PG8_WAIT_V(n) asm volatile("s_waitcnt vmcnt(" #n ")" ::: "memory")
; #define PG8_WAIT_L(n) asm volatile("s_waitcnt lgkmcnt(" #n ")" ::: "memory")
; template <class Epi, class Sched, bool ALIGN_EPI = false, bool SP2 = false>
; __device__ __forceinline__ void gemm_phase(PG8_LAS unsigned char* lds, const Gemm g, const Sched& S, const Epi& E) {
;     ...
;             const bool last = (t == nt - 2);
;             const char* a1 = cA + (size_t)(t + 1) * kstep;
;             const char* a2 = last ? nA : cA + (size_t)(t + 2) * kstep; const char* b2 = last ? nB : cB + (size_t)(t + 2) * kstep;
;             const char* a3 = a2 + kstep; const char* b3 = b2 + kstep;
;             if (last && has_next) S.a_ready(nxt);
;             if constexpr (SP2) {
;             PG8_LDB(B0, 0, 0); PG8_LDB(B1, 0, 1); PG8_SCHED; PG8_LDA(At, 0, 0); PG8_STAGE(PG8_SA(1, 1), a1 + hstep, voffA);
;             PG8_WAIT_V(8); PG8_WAIT_L(0); PG8_BAR; PG8_MMA(0, 0, At, B0); PG8_MMA(0, 1, At, B1); PG8_BAR; PG8_SCHED;
;             PG8_LDA(At, 0, 1); PG8_STAGE(PG8_SB(0, 0), b2, voffB); PG8_STAGE(PG8_SB(0, 1), b2 + hstep, voffB); PG8_STAGE(PG8_SA(0, 0), a2, voffA);
;             PG8_WAIT_V(8); PG8_WAIT_L(0); PG8_BAR; PG8_MMA(1, 0, At, B0); PG8_MMA(1, 1, At, B1); PG8_BAR; PG8_SCHED;
.LBB0_353:
	s_ashr_i32 s41, s40, 31
	s_lshl_b64 s[42:43], s[40:41], 20
	s_add_u32 s42, s14, s42
	s_addc_u32 s43, s15, s43
	s_and_b64 s[46:47], s[36:37], exec
	s_cselect_b32 s41, s43, s49
	s_cselect_b32 s55, s42, s48
	s_ashr_i32 s39, s38, 31
	s_lshl_b64 s[46:47], s[38:39], 20
	s_add_u32 s46, s8, s46
	s_addc_u32 s47, s9, s47
	s_and_b64 s[58:59], s[36:37], exec
	s_cselect_b32 s39, s47, s75
	s_cselect_b32 s58, s46, s74
	s_add_u32 s48, s48, 0x80080
	s_addc_u32 s49, s49, 0
	s_add_u32 s59, s74, 0x100
	v_mov_b32_e32 v0, 0
	s_addc_u32 s63, s75, 0
	s_mov_b32 s71, -2
	s_add_u32 s68, s48, 0xfff80080
	s_addc_u32 s69, s49, -1
	s_add_i32 s78, 0, 0x10000
	s_cmp_eq_u32 s71, 28
	s_cselect_b32 s77, s41, s69
	s_cselect_b32 s76, s55, s68
	v_add_u32_e32 v150, s78, v139
	s_cselect_b32 s75, s39, s63
	s_cselect_b32 s74, s58, s59
	s_add_i32 s68, 0, 0x14000
	ds_read_b128 v[142:145], v150
	ds_read_b128 v[146:149], v150 offset:1024
	ds_read_b128 v[156:159], v150 offset:2048
	ds_read_b128 v[160:163], v150 offset:3072
	v_add_u32_e32 v150, s68, v139
	ds_read_b128 v[164:167], v150
	ds_read_b128 v[168:171], v150 offset:1024
	ds_read_b128 v[172:175], v150 offset:2048
	ds_read_b128 v[192:195], v150 offset:3072
	v_lshl_add_u64 v[150:151], s[48:49], 0, v[134:135]
	s_add_i32 m0, s16, 0xc000
	ds_read_b128 v[196:199], v141
	ds_read_b128 v[200:203], v141 offset:1024
	ds_read_b128 v[204:207], v141 offset:2048
	ds_read_b128 v[208:211], v141 offset:3072
	ds_read_b128 v[212:215], v141 offset:4096
	ds_read_b128 v[216:219], v141 offset:5120
	ds_read_b128 v[220:223], v141 offset:6144
	ds_read_b128 v[224:227], v141 offset:7168
	global_load_lds_dwordx4 v[150:151], off
	v_lshl_add_u64 v[150:151], s[48:49], 0, v[136:137]
	s_add_i32 m0, s16, 0xe000
	s_nop 0
	global_load_lds_dwordx4 v[150:151], off
	s_waitcnt vmcnt(8)
	s_waitcnt lgkmcnt(0)
	s_setprio 1
	s_barrier
	v_mfma_f32_16x16x32_bf16 v[124:127], v[142:145], v[196:199], 0
	v_mfma_f32_16x16x32_bf16 v[120:123], v[156:159], v[196:199], 0
	v_mfma_f32_16x16x32_bf16 v[116:119], v[142:145], v[204:207], 0
	v_mfma_f32_16x16x32_bf16 v[108:111], v[156:159], v[204:207], 0
	v_mfma_f32_16x16x32_bf16 v[100:103], v[142:145], v[212:215], 0
	v_mfma_f32_16x16x32_bf16 v[92:95], v[156:159], v[212:215], 0
	v_mfma_f32_16x16x32_bf16 v[84:87], v[142:145], v[220:223], 0
	v_mfma_f32_16x16x32_bf16 v[76:79], v[156:159], v[220:223], 0
	v_mfma_f32_16x16x32_bf16 v[124:127], v[146:149], v[200:203], v[124:127]
	v_mfma_f32_16x16x32_bf16 v[120:123], v[160:163], v[200:203], v[120:123]
	v_mfma_f32_16x16x32_bf16 v[116:119], v[146:149], v[208:211], v[116:119]
	v_mfma_f32_16x16x32_bf16 v[108:111], v[160:163], v[208:211], v[108:111]
	v_mfma_f32_16x16x32_bf16 v[100:103], v[146:149], v[216:219], v[100:103]
	v_mfma_f32_16x16x32_bf16 v[92:95], v[160:163], v[216:219], v[92:95]
	v_mfma_f32_16x16x32_bf16 v[84:87], v[146:149], v[224:227], v[84:87]
	v_mfma_f32_16x16x32_bf16 v[76:79], v[160:163], v[224:227], v[76:79]
	v_mfma_f32_16x16x32_bf16 v[112:115], v[164:167], v[196:199], 0
	v_mfma_f32_16x16x32_bf16 v[104:107], v[172:175], v[196:199], 0
	v_mfma_f32_16x16x32_bf16 v[96:99], v[164:167], v[204:207], 0
	v_mfma_f32_16x16x32_bf16 v[88:91], v[172:175], v[204:207], 0
	v_mfma_f32_16x16x32_bf16 v[80:83], v[164:167], v[212:215], 0
	v_mfma_f32_16x16x32_bf16 v[72:75], v[172:175], v[212:215], 0
	v_mfma_f32_16x16x32_bf16 v[68:71], v[164:167], v[220:223], 0
	v_mfma_f32_16x16x32_bf16 v[64:67], v[172:175], v[220:223], 0
	v_mfma_f32_16x16x32_bf16 v[112:115], v[168:171], v[200:203], v[112:115]
	v_mfma_f32_16x16x32_bf16 v[104:107], v[192:195], v[200:203], v[104:107]
	v_mfma_f32_16x16x32_bf16 v[96:99], v[168:171], v[208:211], v[96:99]
	v_mfma_f32_16x16x32_bf16 v[88:91], v[192:195], v[208:211], v[88:91]
	v_mfma_f32_16x16x32_bf16 v[80:83], v[168:171], v[216:219], v[80:83]
	v_mfma_f32_16x16x32_bf16 v[72:75], v[192:195], v[216:219], v[72:75]
	v_mfma_f32_16x16x32_bf16 v[68:71], v[168:171], v[224:227], v[68:71]
	v_mfma_f32_16x16x32_bf16 v[64:67], v[192:195], v[224:227], v[64:67]
	s_barrier
	s_setprio 0
	s_add_i32 s69, s78, s0
	v_lshl_add_u64 v[150:151], s[74:75], 0, v[152:153]
	s_mov_b32 m0, s69
	ds_read_b128 v[196:199], v141 offset:16384
	ds_read_b128 v[200:203], v141 offset:17408
	ds_read_b128 v[204:207], v141 offset:18432
	ds_read_b128 v[208:211], v141 offset:19456
	ds_read_b128 v[212:215], v141 offset:20480
	ds_read_b128 v[216:219], v141 offset:21504
	ds_read_b128 v[220:223], v141 offset:22528
	ds_read_b128 v[224:227], v141 offset:23552
	global_load_lds_dwordx4 v[150:151], off
	s_add_i32 m0, s69, 0x2000
	s_add_u32 s78, s74, 0x80000
	v_lshl_add_u64 v[182:183], s[74:75], 0, v[132:133]
	s_addc_u32 s79, s75, 0
	s_add_i32 s68, s68, s0
	global_load_lds_dwordx4 v[182:183], off
	v_lshl_add_u64 v[184:185], s[78:79], 0, v[152:153]
	s_mov_b32 m0, s68
	v_lshl_add_u64 v[188:189], s[76:77], 0, v[130:131]
	global_load_lds_dwordx4 v[184:185], off
	v_lshl_add_u64 v[184:185], s[78:79], 0, v[132:133]
	s_add_i32 m0, s68, 0x2000
	s_nop 0
	global_load_lds_dwordx4 v[184:185], off
	v_lshl_add_u64 v[184:185], s[76:77], 0, v[128:129]
	s_mov_b32 m0, s16
	s_nop 0
	global_load_lds_dwordx4 v[184:185], off
	s_mov_b32 m0, s17
	s_nop 0
	global_load_lds_dwordx4 v[188:189], off
	s_waitcnt vmcnt(8)
	s_waitcnt lgkmcnt(0)
	s_setprio 1
	s_barrier
; #define PG8_STAGE(bufoff, gbase, voff) do { _Pragma("unroll") for (int _i = 0; _i < 2; ++_i) \
;         __builtin_amdgcn_global_load_lds((const unsigned*)((const char*)(gbase) + (voff)[_i]), (PG8_LAS unsigned*)(lds + (bufoff) + ldsw + _i * 8192), 16, 0, 0); } while (0)
; #define PG8_LDA(dst, b, h) do { _Pragma("unroll") for (int m = 0; m < 4; ++m) _Pragma("unroll") for (int k = 0; k < 2; ++k) dst[m][k] = *(const PG8_LAS bf16x8*)(lds + PG8_SA(b, h) + aoff + m * 2048 + k * 1024); } while (0)
; #define PG8_LDB(dst, b, h) do { _Pragma("unroll") for (int n = 0; n < 2; ++n) _Pragma("unroll") for (int k = 0; k < 2; ++k) dst[n][k] = *(const PG8_LAS bf16x8*)(lds + PG8_SB(b, h) + boff + n * 2048 + k * 1024); } while (0)
; #define PG8_MMA(ai, bj, At, Bt) do { __builtin_amdgcn_s_setprio(1); _Pragma("unroll") for (int m = 0; m < 4; ++m) _Pragma("unroll") for (int n = 0; n < 2; ++n) _Pragma("unroll") for (int k = 0; k < 2; ++k) \
;         acc[ai][bj][m][n] = __builtin_amdgcn_mfma_f32_16x16x32_bf16(Bt[n][k], At[m][k], acc[ai][bj][m][n], 0, 0, 0); __builtin_amdgcn_s_setprio(0); } while (0)
; #define PG8_WAIT_V(n) asm volatile("s_waitcnt vmcnt(" #n ")" ::: "memory")
; #define PG8_WAIT_L(n) asm volatile("s_waitcnt lgkmcnt(" #n ")" ::: "memory")
; #define PG8_BAR __builtin_amdgcn_s_barrier()
; #define PG8_SCHED __builtin_amdgcn_sched_barrier(0)
; template <class Epi, class Sched, bool ALIGN_EPI = false, bool SP2 = false>
; __device__ __forceinline__ void gemm_phase(PG8_LAS unsigned char* lds, const Gemm g, const Sched& S, const Epi& E) {
;     ...
;             PG8_WAIT_V(8); PG8_WAIT_L(0); PG8_BAR; PG8_MMA(1, 0, At, B0); PG8_MMA(1, 1, At, B1); PG8_BAR; PG8_SCHED;
;             PG8_LDB(B0, 1, 0); PG8_LDB(B1, 1, 1); PG8_SCHED; PG8_LDA(At, 1, 0); PG8_STAGE(PG8_SA(0, 1), a2 + hstep, voffA);
;             PG8_WAIT_V(8); PG8_WAIT_L(0); PG8_BAR; PG8_MMA(0, 0, At, B0); PG8_MMA(0, 1, At, B1); PG8_BAR; PG8_SCHED;
;             PG8_LDA(At, 1, 1); PG8_STAGE(PG8_SB(1, 0), b3, voffB); PG8_STAGE(PG8_SB(1, 1), b3 + hstep, voffB); PG8_STAGE(PG8_SA(1, 0), a3, voffA);
	v_mfma_f32_16x16x32_bf16 v[60:63], v[142:145], v[196:199], 0
	v_mfma_f32_16x16x32_bf16 v[56:59], v[156:159], v[196:199], 0
	v_mfma_f32_16x16x32_bf16 v[52:55], v[142:145], v[204:207], 0
	v_mfma_f32_16x16x32_bf16 v[44:47], v[156:159], v[204:207], 0
	v_mfma_f32_16x16x32_bf16 v[36:39], v[142:145], v[212:215], 0
	v_mfma_f32_16x16x32_bf16 v[28:31], v[156:159], v[212:215], 0
	v_mfma_f32_16x16x32_bf16 v[20:23], v[142:145], v[220:223], 0
	v_mfma_f32_16x16x32_bf16 v[12:15], v[156:159], v[220:223], 0
	v_mfma_f32_16x16x32_bf16 v[60:63], v[146:149], v[200:203], v[60:63]
	v_mfma_f32_16x16x32_bf16 v[56:59], v[160:163], v[200:203], v[56:59]
	v_mfma_f32_16x16x32_bf16 v[52:55], v[146:149], v[208:211], v[52:55]
	v_mfma_f32_16x16x32_bf16 v[44:47], v[160:163], v[208:211], v[44:47]
	v_mfma_f32_16x16x32_bf16 v[36:39], v[146:149], v[216:219], v[36:39]
	v_mfma_f32_16x16x32_bf16 v[28:31], v[160:163], v[216:219], v[28:31]
	v_mfma_f32_16x16x32_bf16 v[20:23], v[146:149], v[224:227], v[20:23]
	v_mfma_f32_16x16x32_bf16 v[12:15], v[160:163], v[224:227], v[12:15]
	v_mfma_f32_16x16x32_bf16 v[48:51], v[164:167], v[196:199], 0
	v_mfma_f32_16x16x32_bf16 v[40:43], v[172:175], v[196:199], 0
	v_mfma_f32_16x16x32_bf16 v[32:35], v[164:167], v[204:207], 0
	v_mfma_f32_16x16x32_bf16 v[24:27], v[172:175], v[204:207], 0
	v_mfma_f32_16x16x32_bf16 v[16:19], v[164:167], v[212:215], 0
	v_mfma_f32_16x16x32_bf16 v[8:11], v[172:175], v[212:215], 0
	v_mfma_f32_16x16x32_bf16 v[4:7], v[164:167], v[220:223], 0
	v_mfma_f32_16x16x32_bf16 v[0:3], v[172:175], v[220:223], 0
	v_mfma_f32_16x16x32_bf16 v[48:51], v[168:171], v[200:203], v[48:51]
	v_mfma_f32_16x16x32_bf16 v[40:43], v[192:195], v[200:203], v[40:43]
	v_mfma_f32_16x16x32_bf16 v[32:35], v[168:171], v[208:211], v[32:35]
	v_mfma_f32_16x16x32_bf16 v[24:27], v[192:195], v[208:211], v[24:27]
	v_mfma_f32_16x16x32_bf16 v[16:19], v[168:171], v[216:219], v[16:19]
	v_mfma_f32_16x16x32_bf16 v[8:11], v[192:195], v[216:219], v[8:11]
	v_mfma_f32_16x16x32_bf16 v[4:7], v[168:171], v[224:227], v[4:7]
	v_mfma_f32_16x16x32_bf16 v[0:3], v[192:195], v[224:227], v[0:3]
	s_barrier
	s_setprio 0
	v_add_u32_e32 v155, s93, v139
	s_add_i32 s68, 0, 0x1c000
	ds_read_b128 v[142:145], v155
	ds_read_b128 v[146:149], v155 offset:1024
	ds_read_b128 v[156:159], v155 offset:2048
	ds_read_b128 v[160:163], v155 offset:3072
	v_add_u32_e32 v155, s68, v139
	ds_read_b128 v[164:167], v155
	ds_read_b128 v[168:171], v155 offset:1024
	ds_read_b128 v[172:175], v155 offset:2048
	ds_read_b128 v[192:195], v155 offset:3072
	s_add_u32 s76, s76, 0x80000
	s_addc_u32 s77, s77, 0
	s_mov_b32 m0, s22
	v_lshl_add_u64 v[190:191], s[76:77], 0, v[128:129]
	ds_read_b128 v[196:199], v141 offset:32768
	ds_read_b128 v[200:203], v141 offset:33792
	ds_read_b128 v[204:207], v141 offset:34816
	ds_read_b128 v[208:211], v141 offset:35840
	ds_read_b128 v[212:215], v141 offset:36864
	ds_read_b128 v[216:219], v141 offset:37888
	ds_read_b128 v[220:223], v141 offset:38912
	ds_read_b128 v[224:227], v141 offset:39936
	global_load_lds_dwordx4 v[190:191], off
	v_lshl_add_u64 v[190:191], s[76:77], 0, v[130:131]
	s_mov_b32 m0, s23
	s_nop 0
	global_load_lds_dwordx4 v[190:191], off
	s_waitcnt vmcnt(8)
	s_waitcnt lgkmcnt(0)
	s_setprio 1
	s_barrier
	v_mfma_f32_16x16x32_bf16 v[124:127], v[142:145], v[196:199], v[124:127]
	v_mfma_f32_16x16x32_bf16 v[120:123], v[156:159], v[196:199], v[120:123]
	v_mfma_f32_16x16x32_bf16 v[116:119], v[142:145], v[204:207], v[116:119]
	v_mfma_f32_16x16x32_bf16 v[108:111], v[156:159], v[204:207], v[108:111]
	v_mfma_f32_16x16x32_bf16 v[100:103], v[142:145], v[212:215], v[100:103]
	v_mfma_f32_16x16x32_bf16 v[92:95], v[156:159], v[212:215], v[92:95]
	v_mfma_f32_16x16x32_bf16 v[84:87], v[142:145], v[220:223], v[84:87]
	v_mfma_f32_16x16x32_bf16 v[76:79], v[156:159], v[220:223], v[76:79]
	v_mfma_f32_16x16x32_bf16 v[124:127], v[146:149], v[200:203], v[124:127]
	v_mfma_f32_16x16x32_bf16 v[120:123], v[160:163], v[200:203], v[120:123]
	v_mfma_f32_16x16x32_bf16 v[116:119], v[146:149], v[208:211], v[116:119]
	v_mfma_f32_16x16x32_bf16 v[108:111], v[160:163], v[208:211], v[108:111]
	v_mfma_f32_16x16x32_bf16 v[100:103], v[146:149], v[216:219], v[100:103]
	v_mfma_f32_16x16x32_bf16 v[92:95], v[160:163], v[216:219], v[92:95]
	v_mfma_f32_16x16x32_bf16 v[84:87], v[146:149], v[224:227], v[84:87]
	v_mfma_f32_16x16x32_bf16 v[76:79], v[160:163], v[224:227], v[76:79]
	v_mfma_f32_16x16x32_bf16 v[112:115], v[164:167], v[196:199], v[112:115]
	v_mfma_f32_16x16x32_bf16 v[104:107], v[172:175], v[196:199], v[104:107]
	v_mfma_f32_16x16x32_bf16 v[96:99], v[164:167], v[204:207], v[96:99]
	v_mfma_f32_16x16x32_bf16 v[88:91], v[172:175], v[204:207], v[88:91]
	v_mfma_f32_16x16x32_bf16 v[80:83], v[164:167], v[212:215], v[80:83]
	v_mfma_f32_16x16x32_bf16 v[72:75], v[172:175], v[212:215], v[72:75]
	v_mfma_f32_16x16x32_bf16 v[68:71], v[164:167], v[220:223], v[68:71]
	v_mfma_f32_16x16x32_bf16 v[64:67], v[172:175], v[220:223], v[64:67]
	v_mfma_f32_16x16x32_bf16 v[112:115], v[168:171], v[200:203], v[112:115]
	v_mfma_f32_16x16x32_bf16 v[104:107], v[192:195], v[200:203], v[104:107]
	v_mfma_f32_16x16x32_bf16 v[96:99], v[168:171], v[208:211], v[96:99]
	v_mfma_f32_16x16x32_bf16 v[88:91], v[192:195], v[208:211], v[88:91]
	v_mfma_f32_16x16x32_bf16 v[80:83], v[168:171], v[216:219], v[80:83]
	v_mfma_f32_16x16x32_bf16 v[72:75], v[192:195], v[216:219], v[72:75]
	v_mfma_f32_16x16x32_bf16 v[68:71], v[168:171], v[224:227], v[68:71]
	v_mfma_f32_16x16x32_bf16 v[64:67], v[192:195], v[224:227], v[64:67]
	s_barrier
; #define PG8_STAGE(bufoff, gbase, voff) do { _Pragma("unroll") for (int _i = 0; _i < 2; ++_i) \
;         __builtin_amdgcn_global_load_lds((const unsigned*)((const char*)(gbase) + (voff)[_i]), (PG8_LAS unsigned*)(lds + (bufoff) + ldsw + _i * 8192), 16, 0, 0); } while (0)
; #define PG8_LDA(dst, b, h) do { _Pragma("unroll") for (int m = 0; m < 4; ++m) _Pragma("unroll") for (int k = 0; k < 2; ++k) dst[m][k] = *(const PG8_LAS bf16x8*)(lds + PG8_SA(b, h) + aoff + m * 2048 + k * 1024); } while (0)
; #define PG8_MMA(ai, bj, At, Bt) do { __builtin_amdgcn_s_setprio(1); _Pragma("unroll") for (int m = 0; m < 4; ++m) _Pragma("unroll") for (int n = 0; n < 2; ++n) _Pragma("unroll") for (int k = 0; k < 2; ++k) \
;         acc[ai][bj][m][n] = __builtin_amdgcn_mfma_f32_16x16x32_bf16(Bt[n][k], At[m][k], acc[ai][bj][m][n], 0, 0, 0); __builtin_amdgcn_s_setprio(0); } while (0)
; #define PG8_WAIT_V(n) asm volatile("s_waitcnt vmcnt(" #n ")" ::: "memory")
; #define PG8_WAIT_L(n) asm volatile("s_waitcnt lgkmcnt(" #n ")" ::: "memory")
; #define PG8_BAR __builtin_amdgcn_s_barrier()
; #define PG8_SCHED __builtin_amdgcn_sched_barrier(0)
; template <class Epi, class Sched, bool ALIGN_EPI = false, bool SP2 = false>
; __device__ __forceinline__ void gemm_phase(PG8_LAS unsigned char* lds, const Gemm g, const Sched& S, const Epi& E) {
;     ...
;             PG8_LDA(At, 1, 1); PG8_STAGE(PG8_SB(1, 0), b3, voffB); PG8_STAGE(PG8_SB(1, 1), b3 + hstep, voffB); PG8_STAGE(PG8_SA(1, 0), a3, voffA);
;             PG8_WAIT_V(8); PG8_WAIT_L(0); PG8_BAR; PG8_MMA(1, 0, At, B0); PG8_MMA(1, 1, At, B1); PG8_BAR; PG8_SCHED;
	s_setprio 0
	s_add_i32 s69, s93, s0
	v_lshl_add_u64 v[150:151], v[150:151], 0, s[18:19]
	s_mov_b32 m0, s69
	ds_read_b128 v[196:199], v141 offset:49152
	ds_read_b128 v[200:203], v141 offset:50176
	ds_read_b128 v[204:207], v141 offset:51200
	ds_read_b128 v[208:211], v141 offset:52224
	ds_read_b128 v[212:215], v141 offset:53248
	ds_read_b128 v[216:219], v141 offset:54272
	ds_read_b128 v[220:223], v141 offset:55296
	ds_read_b128 v[224:227], v141 offset:56320
	global_load_lds_dwordx4 v[150:151], off
	s_add_i32 m0, s69, 0x2000
	s_add_u32 s74, s74, 0x80080
	v_lshl_add_u64 v[150:151], v[182:183], 0, s[18:19]
	s_addc_u32 s75, s75, 0
	s_add_i32 s68, s68, s0
	global_load_lds_dwordx4 v[150:151], off
	v_lshl_add_u64 v[150:151], s[74:75], 0, v[152:153]
	s_mov_b32 m0, s68
	s_nop 0
	global_load_lds_dwordx4 v[150:151], off
	v_lshl_add_u64 v[150:151], s[74:75], 0, v[132:133]
	s_add_i32 m0, s68, 0x2000
	s_nop 0
	global_load_lds_dwordx4 v[150:151], off
	v_lshl_add_u64 v[150:151], v[184:185], 0, s[18:19]
	s_mov_b32 m0, s26
	s_nop 0
	global_load_lds_dwordx4 v[150:151], off
	v_lshl_add_u64 v[150:151], v[188:189], 0, s[18:19]
	s_mov_b32 m0, s34
	s_nop 0
	global_load_lds_dwordx4 v[150:151], off
	s_waitcnt vmcnt(8)
	s_waitcnt lgkmcnt(0)
	s_setprio 1
	s_barrier
	v_mfma_f32_16x16x32_bf16 v[60:63], v[142:145], v[196:199], v[60:63]
	v_mfma_f32_16x16x32_bf16 v[56:59], v[156:159], v[196:199], v[56:59]
	v_mfma_f32_16x16x32_bf16 v[52:55], v[142:145], v[204:207], v[52:55]
	v_mfma_f32_16x16x32_bf16 v[44:47], v[156:159], v[204:207], v[44:47]
	v_mfma_f32_16x16x32_bf16 v[36:39], v[142:145], v[212:215], v[36:39]
	v_mfma_f32_16x16x32_bf16 v[28:31], v[156:159], v[212:215], v[28:31]
	v_mfma_f32_16x16x32_bf16 v[20:23], v[142:145], v[220:223], v[20:23]
	v_mfma_f32_16x16x32_bf16 v[12:15], v[156:159], v[220:223], v[12:15]
	v_mfma_f32_16x16x32_bf16 v[60:63], v[146:149], v[200:203], v[60:63]
	v_mfma_f32_16x16x32_bf16 v[56:59], v[160:163], v[200:203], v[56:59]
	v_mfma_f32_16x16x32_bf16 v[52:55], v[146:149], v[208:211], v[52:55]
	v_mfma_f32_16x16x32_bf16 v[44:47], v[160:163], v[208:211], v[44:47]
	v_mfma_f32_16x16x32_bf16 v[36:39], v[146:149], v[216:219], v[36:39]
	v_mfma_f32_16x16x32_bf16 v[28:31], v[160:163], v[216:219], v[28:31]
	v_mfma_f32_16x16x32_bf16 v[20:23], v[146:149], v[224:227], v[20:23]
	v_mfma_f32_16x16x32_bf16 v[12:15], v[160:163], v[224:227], v[12:15]
	v_mfma_f32_16x16x32_bf16 v[48:51], v[164:167], v[196:199], v[48:51]
	v_mfma_f32_16x16x32_bf16 v[40:43], v[172:175], v[196:199], v[40:43]
	v_mfma_f32_16x16x32_bf16 v[32:35], v[164:167], v[204:207], v[32:35]
	v_mfma_f32_16x16x32_bf16 v[24:27], v[172:175], v[204:207], v[24:27]
	v_mfma_f32_16x16x32_bf16 v[16:19], v[164:167], v[212:215], v[16:19]
	v_mfma_f32_16x16x32_bf16 v[8:11], v[172:175], v[212:215], v[8:11]
	v_mfma_f32_16x16x32_bf16 v[4:7], v[164:167], v[220:223], v[4:7]
	v_mfma_f32_16x16x32_bf16 v[0:3], v[172:175], v[220:223], v[0:3]
	v_mfma_f32_16x16x32_bf16 v[48:51], v[168:171], v[200:203], v[48:51]
	v_mfma_f32_16x16x32_bf16 v[40:43], v[192:195], v[200:203], v[40:43]
	v_mfma_f32_16x16x32_bf16 v[32:35], v[168:171], v[208:211], v[32:35]
	v_mfma_f32_16x16x32_bf16 v[24:27], v[192:195], v[208:211], v[24:27]
	v_mfma_f32_16x16x32_bf16 v[16:19], v[168:171], v[216:219], v[16:19]
	v_mfma_f32_16x16x32_bf16 v[8:11], v[192:195], v[216:219], v[8:11]
	v_mfma_f32_16x16x32_bf16 v[4:7], v[168:171], v[224:227], v[4:7]
	v_mfma_f32_16x16x32_bf16 v[0:3], v[192:195], v[224:227], v[0:3]
	s_barrier
	s_setprio 0
	s_add_i32 s71, s71, 2
	s_add_u32 s48, s48, 0x100
	s_addc_u32 s49, s49, 0
	s_add_u32 s59, s59, 0x100
	s_addc_u32 s63, s63, 0
	s_cmp_gt_u32 s71, 29
	s_cbranch_scc1 .Lpeel_exit_354

; #define PG8_BAR __builtin_amdgcn_s_barrier()
; template <class Epi, class Sched, bool ALIGN_EPI = false, bool SP2 = false>
; __device__ __forceinline__ void gemm_phase(PG8_LAS unsigned char* lds, const Gemm g, const Sched& S, const Epi& E) {
;     ...
;         if constexpr (ALIGN_EPI) { if (wr == 0) PG8_BAR; }
.Lpeel_exit_354:
	s_and_b64 vcc, exec, s[28:29]
	s_movk_i32 s58, 0x5fe
	s_movk_i32 s59, 0x1810
	s_cbranch_vccz .LBB0_357
	s_barrier
